# gdn_local forward substitution: fully unrolled register-resident solve with LDS prefetch ring + DPP pair-sum (replaces divergent exec-masked loops); branch trampolines for range; cg grid.sync skipped
# speedup vs baseline: 1.1695x; 1.0548x over previous
_Z14fwd_megakernel6Params:
	s_load_dwordx16 s[76:91], s[0:1], 0x0
	s_load_dwordx4 s[52:55], s[0:1], 0xa0
	s_load_dwordx8 s[24:31], s[0:1], 0x80
	s_load_dword s59, s[0:1], 0xb0
	v_writelane_b32 v251, s2, 0
	s_add_u32 s2, s0, 0xb0
	s_addc_u32 s3, s1, 0
	v_writelane_b32 v251, s2, 1
	s_waitcnt lgkmcnt(0)
	s_cmp_lg_u32 s54, 0
	v_writelane_b32 v251, s3, 2
	s_cselect_b64 s[2:3], -1, 0
	v_writelane_b32 v251, s2, 3
	s_cmp_eq_u32 s54, 0
	s_nop 0
	v_writelane_b32 v251, s3, 4
	s_branch .LBB0_12
	v_and_b32_e32 v1, 0x3fffffff, v0
	v_cmp_eq_u32_e32 vcc, 0, v1
	s_barrier
	s_and_saveexec_b64 s[2:3], vcc
	s_cbranch_execz .LBB0_11
	v_readlane_b32 s4, v251, 1
	v_readlane_b32 s5, v251, 2
	buffer_wbl2 sc1
	s_load_dwordx2 s[4:5], s[4:5], 0x58
	s_mov_b64 s[6:7], exec
	v_mbcnt_lo_u32_b32 v1, s6, 0
	v_mbcnt_hi_u32_b32 v1, s7, v1
	v_cmp_eq_u32_e32 vcc, 0, v1
	s_waitcnt lgkmcnt(0)
	s_load_dword s10, s[4:5], 0x28
	s_and_saveexec_b64 s[8:9], vcc
	s_cbranch_execz .LBB0_4
	s_bcnt1_i32_b64 s6, s[6:7]
	v_mov_b32_e32 v2, 0
	v_mov_b32_e32 v3, s6
	global_atomic_add v2, v2, v3, s[4:5] offset:32 sc0

.LBB0_451:
	s_or_b64 exec, exec, s[8:9]
	v_lshl_add_u32 v37, v36, 2, v201
	s_barrier
	ds_read_b32 v57, v37
	v_mad_u64_u32 v[36:37], s[8:9], v36, s45, v[34:35]
	v_add_u32_e32 v60, 0x8000, v36
	ds_read2_b32 v[62:63], v60 offset0:128 offset1:193
	v_add_u32_e32 v59, 0x4000, v36
	ds_read2_b32 v[64:65], v59 offset0:64 offset1:129
	v_add_u32_e32 v58, 0x8400, v36
	v_lshlrev_b32_e32 v38, 2, v38
	s_waitcnt lgkmcnt(1)
	v_mul_f32_e32 v37, v57, v62
	ds_write_b32 v36, v37 offset:33280
	ds_read_b32 v37, v39
	v_lshlrev_b32_e32 v39, 2, v41
	s_mov_b32 s0, 1
	s_mov_b32 s3, 0xc400
	s_waitcnt lgkmcnt(0)
	v_mul_f32_e32 v37, v57, v37
	v_mul_f32_e32 v37, v64, v37
	ds_write_b32 v36, v37 offset:16640
	v_add_u32_e32 v37, 0x10400, v39
	ds_read_b32 v37, v37
	v_add_u32_e32 v39, 0x10500, v39
	v_lshlrev_b32_e32 v57, 2, v40
	v_add_u32_e32 v61, 0x10400, v57
	s_waitcnt lgkmcnt(0)
	v_mul_f32_e32 v41, v37, v63
	ds_write_b32 v36, v41 offset:33540
	ds_read_b32 v39, v39
	ds_read2_b32 v[40:41], v58 offset0:2 offset1:67
	s_waitcnt lgkmcnt(1)
	v_mul_f32_e32 v37, v37, v39
	v_mul_f32_e32 v37, v65, v37
	ds_write_b32 v36, v37 offset:16900
	ds_read_b32 v37, v61
	v_add_u32_e32 v39, 0x10500, v57
	v_add_u32_e32 v57, 0x4200, v36
	s_waitcnt lgkmcnt(0)
	v_mul_f32_e32 v40, v37, v40
	ds_write_b32 v36, v40 offset:33800
	ds_read_b32 v39, v39
	ds_read2_b32 v[62:63], v57 offset0:66 offset1:131
	v_add_u32_e32 v40, 0x10400, v38
	v_add_u32_e32 v38, 0x10500, v38
	s_waitcnt lgkmcnt(1)
	v_mul_f32_e32 v37, v37, v39
	s_waitcnt lgkmcnt(0)
	v_mul_f32_e32 v37, v62, v37
	ds_write_b32 v36, v37 offset:17160
	ds_read_b32 v37, v40
	s_waitcnt lgkmcnt(0)
	v_mul_f32_e32 v39, v37, v41
	ds_write_b32 v36, v39 offset:34060
	ds_read_b32 v40, v38
	v_lshl_add_u32 v41, v43, 2, v201
	ds_read2_b32 v[38:39], v58 offset0:132 offset1:197
	s_waitcnt lgkmcnt(1)
	v_mul_f32_e32 v37, v37, v40
	v_mul_f32_e32 v37, v63, v37
	ds_write_b32 v36, v37 offset:17420
	ds_read_b32 v37, v41
	v_add_u32_e32 v40, 0x4400, v36
	s_waitcnt lgkmcnt(0)
	v_mul_f32_e32 v38, v37, v38
	ds_write_b32 v36, v38 offset:34320
	ds_read_b32 v38, v42
	ds_read2_b32 v[40:41], v40 offset0:68 offset1:133
	v_lshlrev_b32_e32 v42, 2, v46
	v_add_u32_e32 v43, 0x10400, v42
	s_waitcnt lgkmcnt(1)
	v_mul_f32_e32 v37, v37, v38
	s_waitcnt lgkmcnt(0)
	v_mul_f32_e32 v37, v40, v37
	ds_write_b32 v36, v37 offset:17680
	ds_read_b32 v37, v43
	v_add_u32_e32 v38, 0x10500, v42
	v_lshlrev_b32_e32 v42, 2, v44
	v_add_u32_e32 v43, 0x10400, v42
	v_add_u32_e32 v44, 0x8800, v36
	s_waitcnt lgkmcnt(0)
	v_mul_f32_e32 v39, v37, v39
	ds_write_b32 v36, v39 offset:34580
	ds_read_b32 v40, v38
	ds_read2_b32 v[38:39], v44 offset0:6 offset1:71
	s_waitcnt lgkmcnt(1)
	v_mul_f32_e32 v37, v37, v40
	v_mul_f32_e32 v37, v41, v37
	ds_write_b32 v36, v37 offset:17940
	ds_read_b32 v37, v43
	v_add_u32_e32 v40, 0x10500, v42
	v_add_u32_e32 v41, 0x4600, v36
	v_lshlrev_b32_e32 v42, 2, v49
	v_add_u32_e32 v43, 0x10400, v42
	s_waitcnt lgkmcnt(0)
	v_mul_f32_e32 v38, v37, v38
	ds_write_b32 v36, v38 offset:34840
	ds_read_b32 v38, v40
	ds_read2_b32 v[40:41], v41 offset0:70 offset1:135
	s_waitcnt lgkmcnt(1)
	v_mul_f32_e32 v37, v37, v38
	s_waitcnt lgkmcnt(0)
	v_mul_f32_e32 v37, v40, v37
	ds_write_b32 v36, v37 offset:18200
	ds_read_b32 v37, v43
	v_add_u32_e32 v38, 0x10500, v42
	v_add_u32_e32 v40, 0x4800, v36
	v_lshlrev_b32_e32 v42, 2, v50
	v_add_u32_e32 v43, 0x10400, v42
	s_waitcnt lgkmcnt(0)
	v_mul_f32_e32 v39, v37, v39
	ds_write_b32 v36, v39 offset:35100
	ds_read_b32 v38, v38
	v_lshl_add_u32 v39, v51, 2, v201
	s_waitcnt lgkmcnt(0)
	v_mul_f32_e32 v37, v37, v38
	v_mul_f32_e32 v37, v41, v37
	ds_write_b32 v36, v37 offset:18460
	ds_read_b32 v37, v39
	ds_read2_b32 v[38:39], v44 offset0:136 offset1:201
	s_waitcnt lgkmcnt(0)
	v_mul_f32_e32 v38, v37, v38
	ds_write_b32 v36, v38 offset:35360
	ds_read_b32 v38, v47
	ds_read2_b32 v[40:41], v40 offset0:72 offset1:137
	s_waitcnt lgkmcnt(1)
	v_mul_f32_e32 v37, v37, v38
	s_waitcnt lgkmcnt(0)
	v_mul_f32_e32 v37, v40, v37
	ds_write_b32 v36, v37 offset:18720
	ds_read_b32 v37, v43
	v_add_u32_e32 v38, 0x10500, v42
	v_lshlrev_b32_e32 v40, 2, v48
	v_add_u32_e32 v42, 0x8c00, v36
	v_lshlrev_b32_e32 v43, 2, v45
	s_waitcnt lgkmcnt(0)
	v_mul_f32_e32 v39, v37, v39
	ds_write_b32 v36, v39 offset:35620
	ds_read_b32 v38, v38
	v_add_u32_e32 v39, 0x10400, v40
	v_add_u32_e32 v40, 0x10500, v40
	v_add_u32_e32 v44, 0x10400, v43
	s_waitcnt lgkmcnt(0)
	v_mul_f32_e32 v37, v37, v38
	v_mul_f32_e32 v37, v41, v37
	ds_write_b32 v36, v37 offset:18980
	ds_read_b32 v37, v39
	ds_read2_b32 v[38:39], v42 offset0:10 offset1:75
	v_add_u32_e32 v41, 0x4a00, v36
	s_waitcnt lgkmcnt(0)
	v_mul_f32_e32 v38, v37, v38
	ds_write_b32 v36, v38 offset:35880
	ds_read_b32 v38, v40
	ds_read2_b32 v[40:41], v41 offset0:74 offset1:139
	s_waitcnt lgkmcnt(1)
	v_mul_f32_e32 v37, v37, v38
	s_waitcnt lgkmcnt(0)
	v_mul_f32_e32 v37, v40, v37
	ds_write_b32 v36, v37 offset:19240
	ds_read_b32 v37, v44
	v_add_u32_e32 v38, 0x10500, v43
	v_add_u32_e32 v40, 0x4c00, v36
	s_waitcnt lgkmcnt(0)
	v_mul_f32_e32 v39, v37, v39
	ds_write_b32 v36, v39 offset:36140
	ds_read_b32 v38, v38
	v_lshl_add_u32 v39, v53, 2, v201
	s_waitcnt lgkmcnt(0)
	v_mul_f32_e32 v37, v37, v38
	v_mul_f32_e32 v37, v41, v37
	ds_write_b32 v36, v37 offset:19500
	ds_read_b32 v37, v39
	ds_read2_b32 v[38:39], v42 offset0:140 offset1:205
	v_lshlrev_b32_e32 v42, 2, v55
	v_add_u32_e32 v43, 0x10400, v42
	v_add_u32_e32 v42, 0x10500, v42
	s_waitcnt lgkmcnt(0)
	v_mul_f32_e32 v38, v37, v38
	ds_write_b32 v36, v38 offset:36400
	ds_read_b32 v38, v52
	ds_read2_b32 v[40:41], v40 offset0:76 offset1:141
	s_waitcnt lgkmcnt(1)
	v_mul_f32_e32 v37, v37, v38
	s_waitcnt lgkmcnt(0)
	v_mul_f32_e32 v37, v40, v37
	ds_write_b32 v36, v37 offset:19760
	ds_read_b32 v37, v43
	v_lshlrev_b32_e32 v38, 2, v56
	v_lshl_add_u32 v40, v35, 2, v201
	v_mad_u64_u32 v[34:35], s[8:9], v35, s45, v[34:35]
	s_waitcnt lgkmcnt(0)
	v_mul_f32_e32 v39, v37, v39
	ds_write_b32 v36, v39 offset:36660
	ds_read_b32 v39, v42
	v_add_u32_e32 v35, 0x10400, v38
	ds_read_b32 v42, v36 offset:36920
	s_waitcnt lgkmcnt(1)
	v_mul_f32_e32 v37, v37, v39
	v_mul_f32_e32 v37, v41, v37
	ds_write_b32 v36, v37 offset:20020
	ds_read_b32 v39, v35
	v_add_u32_e32 v35, 0x10500, v38
	ds_read_b32 v38, v36 offset:20280
	v_ashrrev_i32_e32 v41, 1, v0
	v_cmp_gt_i32_e32 vcc, 64, v41
	s_waitcnt lgkmcnt(1)
	v_mul_f32_e32 v37, v39, v42
	ds_write_b32 v36, v37 offset:36920
	ds_read_b32 v43, v35
	v_and_b32_e32 v42, 1, v0
	v_cndmask_b32_e32 v44, v199, v203, vcc
	v_add_u32_e32 v37, 0x514, v36
	v_add_u32_e32 v35, 0xa28, v36
	s_waitcnt lgkmcnt(0)
	v_mul_f32_e32 v0, v39, v43
	v_mul_f32_e32 v0, v38, v0
	ds_write_b32 v36, v0 offset:20280
	ds_read_b32 v40, v40
	ds_read2st64_b32 v[38:39], v34 offset0:65 offset1:130
	v_lshlrev_b32_e32 v0, 2, v41
	v_mul_u32_u24_e32 v41, 0x104, v42
	v_and_b32_e32 v45, 0xfc, v0
	v_or_b32_e32 v43, 2, v42
	s_waitcnt lgkmcnt(0)
	v_mul_f32_e32 v39, v40, v39
	ds_write_b32 v34, v39 offset:33280
	ds_read_b32 v39, v54
	v_cmp_eq_u32_e32 vcc, 0, v42
	v_or_b32_e32 v0, v44, v45
	v_add3_u32 v44, v41, v45, v44
	v_lshl_or_b32 v45, v42, 2, v204
	s_waitcnt lgkmcnt(0)
	v_mul_f32_e32 v39, v40, v39
	v_mul_f32_e32 v38, v38, v39
	ds_write_b32 v34, v38 offset:16640
	s_waitcnt lgkmcnt(0)
	s_barrier
	s_mov_b32 s4, 0x55555555
	s_mov_b32 s5, 0x55555555
	s_mov_b32 s8, 0xaaaaaaaa
	s_mov_b32 s9, 0xaaaaaaaa
	ds_read_b32 v136, v44 offset:0
	ds_read_b32 v137, v44 offset:520
	ds_read_b32 v138, v44 offset:1040
	ds_read_b32 v139, v44 offset:1560
	ds_read_b32 v140, v44 offset:2080
	ds_read_b32 v141, v44 offset:2600
	ds_read_b32 v142, v44 offset:3120
	ds_read_b32 v143, v44 offset:3640
	ds_read_b32 v144, v44 offset:4160
	ds_read_b32 v145, v44 offset:4680
	ds_read_b32 v146, v44 offset:5200
	ds_read_b32 v147, v44 offset:5720
	ds_read_b32 v148, v44 offset:6240
	ds_read_b32 v149, v44 offset:6760
	ds_read_b32 v150, v44 offset:7280
	s_waitcnt lgkmcnt(0)
	ds_read_b32 v151, v44 offset:7800
	ds_read_b32 v152, v44 offset:8320
	ds_read_b32 v153, v44 offset:8840
	ds_read_b32 v154, v44 offset:9360
	ds_read_b32 v155, v44 offset:9880
	ds_read_b32 v156, v44 offset:10400
	ds_read_b32 v157, v44 offset:10920
	ds_read_b32 v158, v44 offset:11440
	ds_read_b32 v159, v44 offset:11960
	ds_read_b32 v160, v44 offset:12480
	ds_read_b32 v161, v44 offset:13000
	ds_read_b32 v162, v44 offset:13520
	ds_read_b32 v163, v44 offset:14040
	ds_read_b32 v164, v44 offset:14560
	ds_read_b32 v165, v44 offset:15080
	ds_read_b32 v166, v44 offset:15600
	ds_read_b32 v167, v44 offset:16120
	s_waitcnt lgkmcnt(0)
	v_add_u32_e32 v227, 0x0, v45
	ds_read2_b32 v[168:169], v227 offset0:0 offset1:2
	v_add_u32_e32 v228, 0x100, v45
	ds_read2_b32 v[170:171], v228 offset0:0 offset1:2
	v_add_u32_e32 v229, 0x200, v45
	ds_read2_b32 v[172:173], v229 offset0:0 offset1:2
	v_add_u32_e32 v226, 0x300, v45
	ds_read2_b32 v[174:175], v226 offset0:0 offset1:2
	v_add_u32_e32 v227, 0x400, v45
	ds_read2_b32 v[176:177], v227 offset0:0 offset1:2
	ds_read2_b32 v[178:179], v227 offset0:4 offset1:6
	v_add_u32_e32 v228, 0x500, v45
	ds_read2_b32 v[180:181], v228 offset0:0 offset1:2
	ds_read2_b32 v[210:211], v228 offset0:4 offset1:6
	v_add_u32_e32 v229, 0x600, v45
	ds_read2_b32 v[212:213], v229 offset0:0 offset1:2
	ds_read2_b32 v[214:215], v229 offset0:4 offset1:6
	v_add_u32_e32 v226, 0x700, v45
	ds_read2_b32 v[216:217], v226 offset0:0 offset1:2
	ds_read2_b32 v[224:225], v226 offset0:4 offset1:6
	s_waitcnt lgkmcnt(11)
	v_mul_f32_e32 v230, v168, v136
	v_mul_f32_e32 v231, v169, v137
	v_add_f32_e32 v230, v230, v231
	s_nop 1
	v_add_f32_dpp v232, v230, v230 quad_perm:[1,0,3,2] row_mask:0xf bank_mask:0xf
	v_sub_f32_e32 v233, v136, v232
	v_cndmask_b32_e64 v136, v136, v233, s[8:9]
	v_add_u32_e32 v227, 0x800, v45
	ds_read2_b32 v[168:169], v227 offset0:0 offset1:2
	s_waitcnt lgkmcnt(11)
	v_mul_f32_e32 v230, v170, v136
	v_mul_f32_e32 v231, v171, v137
	v_add_f32_e32 v230, v230, v231
	s_nop 1
	v_add_f32_dpp v232, v230, v230 quad_perm:[1,0,3,2] row_mask:0xf bank_mask:0xf
	v_sub_f32_e32 v233, v137, v232
	v_cndmask_b32_e64 v137, v137, v233, s[4:5]
	ds_read2_b32 v[170:171], v227 offset0:4 offset1:6
	s_waitcnt lgkmcnt(11)
	v_mul_f32_e32 v230, v172, v136
	v_mul_f32_e32 v231, v173, v137
	v_add_f32_e32 v230, v230, v231
	s_nop 1
	v_add_f32_dpp v232, v230, v230 quad_perm:[1,0,3,2] row_mask:0xf bank_mask:0xf
	v_sub_f32_e32 v233, v137, v232
	v_cndmask_b32_e64 v137, v137, v233, s[8:9]
	ds_read2_b32 v[172:173], v227 offset0:8 offset1:10
	s_waitcnt lgkmcnt(11)
	v_mul_f32_e32 v230, v174, v136
	v_mul_f32_e32 v231, v175, v137
	v_add_f32_e32 v230, v230, v231
	s_nop 1
	v_add_f32_dpp v232, v230, v230 quad_perm:[1,0,3,2] row_mask:0xf bank_mask:0xf
	v_sub_f32_e32 v233, v138, v232
	v_cndmask_b32_e64 v138, v138, v233, s[4:5]
	v_add_u32_e32 v228, 0x900, v45
	ds_read2_b32 v[174:175], v228 offset0:0 offset1:2
	s_waitcnt lgkmcnt(11)
	v_mul_f32_e32 v230, v176, v136
	v_mul_f32_e32 v231, v177, v137
	ds_read2_b32 v[176:177], v228 offset0:4 offset1:6
	s_waitcnt lgkmcnt(11)
	v_fmac_f32_e32 v230, v178, v138
	v_fmac_f32_e32 v231, v179, v139
	v_add_f32_e32 v230, v230, v231
	s_nop 1
	v_add_f32_dpp v232, v230, v230 quad_perm:[1,0,3,2] row_mask:0xf bank_mask:0xf
	v_sub_f32_e32 v233, v138, v232
	v_cndmask_b32_e64 v138, v138, v233, s[8:9]
	ds_read2_b32 v[178:179], v228 offset0:8 offset1:10
	s_waitcnt lgkmcnt(11)
	v_mul_f32_e32 v230, v180, v136
	v_mul_f32_e32 v231, v181, v137
	v_add_u32_e32 v229, 0xa00, v45
	ds_read2_b32 v[180:181], v229 offset0:0 offset1:2
	s_waitcnt lgkmcnt(11)
	v_fmac_f32_e32 v230, v210, v138
	v_fmac_f32_e32 v231, v211, v139
	v_add_f32_e32 v230, v230, v231
	s_nop 1
	v_add_f32_dpp v232, v230, v230 quad_perm:[1,0,3,2] row_mask:0xf bank_mask:0xf
	v_sub_f32_e32 v233, v139, v232
	v_cndmask_b32_e64 v139, v139, v233, s[4:5]
	ds_read2_b32 v[210:211], v229 offset0:4 offset1:6
	s_waitcnt lgkmcnt(11)
	v_mul_f32_e32 v230, v212, v136
	v_mul_f32_e32 v231, v213, v137
	ds_read2_b32 v[212:213], v229 offset0:8 offset1:10
	s_waitcnt lgkmcnt(11)
	v_fmac_f32_e32 v230, v214, v138
	v_fmac_f32_e32 v231, v215, v139
	v_add_f32_e32 v230, v230, v231
	s_nop 1
	v_add_f32_dpp v232, v230, v230 quad_perm:[1,0,3,2] row_mask:0xf bank_mask:0xf
	v_sub_f32_e32 v233, v139, v232
	v_cndmask_b32_e64 v139, v139, v233, s[8:9]
	v_add_u32_e32 v226, 0xb00, v45
	ds_read2_b32 v[214:215], v226 offset0:0 offset1:2
	s_waitcnt lgkmcnt(11)
	v_mul_f32_e32 v230, v216, v136
	v_mul_f32_e32 v231, v217, v137
	ds_read2_b32 v[216:217], v226 offset0:4 offset1:6
	s_waitcnt lgkmcnt(11)
	v_fmac_f32_e32 v230, v224, v138
	v_fmac_f32_e32 v231, v225, v139
	v_add_f32_e32 v230, v230, v231
	s_nop 1
	v_add_f32_dpp v232, v230, v230 quad_perm:[1,0,3,2] row_mask:0xf bank_mask:0xf
	v_sub_f32_e32 v233, v140, v232
	v_cndmask_b32_e64 v140, v140, v233, s[4:5]
	ds_read2_b32 v[224:225], v226 offset0:8 offset1:10
	s_waitcnt lgkmcnt(11)
	v_mul_f32_e32 v230, v168, v136
	v_mul_f32_e32 v231, v169, v137
	v_add_u32_e32 v227, 0xc00, v45
	ds_read2_b32 v[168:169], v227 offset0:0 offset1:2
	s_waitcnt lgkmcnt(11)
	v_fmac_f32_e32 v230, v170, v138
	v_fmac_f32_e32 v231, v171, v139
	ds_read2_b32 v[170:171], v227 offset0:4 offset1:6
	s_waitcnt lgkmcnt(11)
	v_fmac_f32_e32 v230, v172, v140
	v_fmac_f32_e32 v231, v173, v141
	v_add_f32_e32 v230, v230, v231
	s_nop 1
	v_add_f32_dpp v232, v230, v230 quad_perm:[1,0,3,2] row_mask:0xf bank_mask:0xf
	v_sub_f32_e32 v233, v140, v232
	v_cndmask_b32_e64 v140, v140, v233, s[8:9]
	ds_read2_b32 v[172:173], v227 offset0:8 offset1:10
	s_waitcnt lgkmcnt(11)
	v_mul_f32_e32 v230, v174, v136
	v_mul_f32_e32 v231, v175, v137
	ds_read2_b32 v[174:175], v227 offset0:12 offset1:14
	s_waitcnt lgkmcnt(11)
	v_fmac_f32_e32 v230, v176, v138
	v_fmac_f32_e32 v231, v177, v139
	v_add_u32_e32 v228, 0xd00, v45
	ds_read2_b32 v[176:177], v228 offset0:0 offset1:2
	s_waitcnt lgkmcnt(11)
	v_fmac_f32_e32 v230, v178, v140
	v_fmac_f32_e32 v231, v179, v141
	v_add_f32_e32 v230, v230, v231
	s_nop 1
	v_add_f32_dpp v232, v230, v230 quad_perm:[1,0,3,2] row_mask:0xf bank_mask:0xf
	v_sub_f32_e32 v233, v141, v232
	v_cndmask_b32_e64 v141, v141, v233, s[4:5]
	ds_read2_b32 v[178:179], v228 offset0:4 offset1:6
	s_waitcnt lgkmcnt(11)
	v_mul_f32_e32 v230, v180, v136
	v_mul_f32_e32 v231, v181, v137
	ds_read2_b32 v[180:181], v228 offset0:8 offset1:10
	s_waitcnt lgkmcnt(11)
	v_fmac_f32_e32 v230, v210, v138
	v_fmac_f32_e32 v231, v211, v139
	ds_read2_b32 v[210:211], v228 offset0:12 offset1:14
	s_waitcnt lgkmcnt(11)
	v_fmac_f32_e32 v230, v212, v140
	v_fmac_f32_e32 v231, v213, v141
	v_add_f32_e32 v230, v230, v231
	s_nop 1
	v_add_f32_dpp v232, v230, v230 quad_perm:[1,0,3,2] row_mask:0xf bank_mask:0xf
	v_sub_f32_e32 v233, v141, v232
	v_cndmask_b32_e64 v141, v141, v233, s[8:9]
	v_add_u32_e32 v229, 0xe00, v45
	ds_read2_b32 v[212:213], v229 offset0:0 offset1:2
	s_waitcnt lgkmcnt(11)
	v_mul_f32_e32 v230, v214, v136
	v_mul_f32_e32 v231, v215, v137
	ds_read2_b32 v[214:215], v229 offset0:4 offset1:6
	s_waitcnt lgkmcnt(11)
	v_fmac_f32_e32 v230, v216, v138
	v_fmac_f32_e32 v231, v217, v139
	ds_read2_b32 v[216:217], v229 offset0:8 offset1:10
	s_waitcnt lgkmcnt(11)
	v_fmac_f32_e32 v230, v224, v140
	v_fmac_f32_e32 v231, v225, v141
	v_add_f32_e32 v230, v230, v231
	s_nop 1
	v_add_f32_dpp v232, v230, v230 quad_perm:[1,0,3,2] row_mask:0xf bank_mask:0xf
	v_sub_f32_e32 v233, v142, v232
	v_cndmask_b32_e64 v142, v142, v233, s[4:5]
	ds_read2_b32 v[224:225], v229 offset0:12 offset1:14
	s_waitcnt lgkmcnt(11)
	v_mul_f32_e32 v230, v168, v136
	v_mul_f32_e32 v231, v169, v137
	v_add_u32_e32 v226, 0xf00, v45
	ds_read2_b32 v[168:169], v226 offset0:0 offset1:2
	s_waitcnt lgkmcnt(11)
	v_fmac_f32_e32 v230, v170, v138
	v_fmac_f32_e32 v231, v171, v139
	ds_read2_b32 v[170:171], v226 offset0:4 offset1:6
	s_waitcnt lgkmcnt(11)
	v_fmac_f32_e32 v230, v172, v140
	v_fmac_f32_e32 v231, v173, v141
	ds_read2_b32 v[172:173], v226 offset0:8 offset1:10
	s_waitcnt lgkmcnt(11)
	v_fmac_f32_e32 v230, v174, v142
	v_fmac_f32_e32 v231, v175, v143
	v_add_f32_e32 v230, v230, v231
	s_nop 1
	v_add_f32_dpp v232, v230, v230 quad_perm:[1,0,3,2] row_mask:0xf bank_mask:0xf
	v_sub_f32_e32 v233, v142, v232
	v_cndmask_b32_e64 v142, v142, v233, s[8:9]
	ds_read2_b32 v[174:175], v226 offset0:12 offset1:14
	s_waitcnt lgkmcnt(11)
	v_mul_f32_e32 v230, v176, v136
	v_mul_f32_e32 v231, v177, v137
	v_add_u32_e32 v227, 0x1000, v45
	ds_read2_b32 v[176:177], v227 offset0:0 offset1:2
	s_waitcnt lgkmcnt(11)
	v_fmac_f32_e32 v230, v178, v138
	v_fmac_f32_e32 v231, v179, v139
	ds_read2_b32 v[178:179], v227 offset0:4 offset1:6
	s_waitcnt lgkmcnt(11)
	v_fmac_f32_e32 v230, v180, v140
	v_fmac_f32_e32 v231, v181, v141
	ds_read2_b32 v[180:181], v227 offset0:8 offset1:10
	s_waitcnt lgkmcnt(11)
	v_fmac_f32_e32 v230, v210, v142
	v_fmac_f32_e32 v231, v211, v143
	v_add_f32_e32 v230, v230, v231
	s_nop 1
	v_add_f32_dpp v232, v230, v230 quad_perm:[1,0,3,2] row_mask:0xf bank_mask:0xf
	v_sub_f32_e32 v233, v143, v232
	v_cndmask_b32_e64 v143, v143, v233, s[4:5]
	ds_read2_b32 v[210:211], v227 offset0:12 offset1:14
	s_waitcnt lgkmcnt(11)
	v_mul_f32_e32 v230, v212, v136
	v_mul_f32_e32 v231, v213, v137
	ds_read2_b32 v[212:213], v227 offset0:16 offset1:18
	s_waitcnt lgkmcnt(11)
	v_fmac_f32_e32 v230, v214, v138
	v_fmac_f32_e32 v231, v215, v139
	v_add_u32_e32 v228, 0x1100, v45
	ds_read2_b32 v[214:215], v228 offset0:0 offset1:2
	s_waitcnt lgkmcnt(11)
	v_fmac_f32_e32 v230, v216, v140
	v_fmac_f32_e32 v231, v217, v141
	ds_read2_b32 v[216:217], v228 offset0:4 offset1:6
	s_waitcnt lgkmcnt(11)
	v_fmac_f32_e32 v230, v224, v142
	v_fmac_f32_e32 v231, v225, v143
	v_add_f32_e32 v230, v230, v231
	s_nop 1
	v_add_f32_dpp v232, v230, v230 quad_perm:[1,0,3,2] row_mask:0xf bank_mask:0xf
	v_sub_f32_e32 v233, v143, v232
	v_cndmask_b32_e64 v143, v143, v233, s[8:9]
	ds_read2_b32 v[224:225], v228 offset0:8 offset1:10
	s_waitcnt lgkmcnt(11)
	v_mul_f32_e32 v230, v168, v136
	v_mul_f32_e32 v231, v169, v137
	ds_read2_b32 v[168:169], v228 offset0:12 offset1:14
	s_waitcnt lgkmcnt(11)
	v_fmac_f32_e32 v230, v170, v138
	v_fmac_f32_e32 v231, v171, v139
	ds_read2_b32 v[170:171], v228 offset0:16 offset1:18
	s_waitcnt lgkmcnt(11)
	v_fmac_f32_e32 v230, v172, v140
	v_fmac_f32_e32 v231, v173, v141
	v_add_u32_e32 v229, 0x1200, v45
	ds_read2_b32 v[172:173], v229 offset0:0 offset1:2
	s_waitcnt lgkmcnt(11)
	v_fmac_f32_e32 v230, v174, v142
	v_fmac_f32_e32 v231, v175, v143
	v_add_f32_e32 v230, v230, v231
	s_nop 1
	v_add_f32_dpp v232, v230, v230 quad_perm:[1,0,3,2] row_mask:0xf bank_mask:0xf
	v_sub_f32_e32 v233, v144, v232
	v_cndmask_b32_e64 v144, v144, v233, s[4:5]
	ds_read2_b32 v[174:175], v229 offset0:4 offset1:6
	s_waitcnt lgkmcnt(11)
	v_mul_f32_e32 v230, v176, v136
	v_mul_f32_e32 v231, v177, v137
	ds_read2_b32 v[176:177], v229 offset0:8 offset1:10
	s_waitcnt lgkmcnt(11)
	v_fmac_f32_e32 v230, v178, v138
	v_fmac_f32_e32 v231, v179, v139
	ds_read2_b32 v[178:179], v229 offset0:12 offset1:14
	s_waitcnt lgkmcnt(11)
	v_fmac_f32_e32 v230, v180, v140
	v_fmac_f32_e32 v231, v181, v141
	ds_read2_b32 v[180:181], v229 offset0:16 offset1:18
	s_waitcnt lgkmcnt(11)
	v_fmac_f32_e32 v230, v210, v142
	v_fmac_f32_e32 v231, v211, v143
	v_add_u32_e32 v226, 0x1300, v45
	ds_read2_b32 v[210:211], v226 offset0:0 offset1:2
	s_waitcnt lgkmcnt(11)
	v_fmac_f32_e32 v230, v212, v144
	v_fmac_f32_e32 v231, v213, v145
	v_add_f32_e32 v230, v230, v231
	s_nop 1
	v_add_f32_dpp v232, v230, v230 quad_perm:[1,0,3,2] row_mask:0xf bank_mask:0xf
	v_sub_f32_e32 v233, v144, v232
	v_cndmask_b32_e64 v144, v144, v233, s[8:9]
	ds_read2_b32 v[212:213], v226 offset0:4 offset1:6
	s_waitcnt lgkmcnt(11)
	v_mul_f32_e32 v230, v214, v136
	v_mul_f32_e32 v231, v215, v137
	ds_read2_b32 v[214:215], v226 offset0:8 offset1:10
	s_waitcnt lgkmcnt(11)
	v_fmac_f32_e32 v230, v216, v138
	v_fmac_f32_e32 v231, v217, v139
	ds_read2_b32 v[216:217], v226 offset0:12 offset1:14
	s_waitcnt lgkmcnt(11)
	v_fmac_f32_e32 v230, v224, v140
	v_fmac_f32_e32 v231, v225, v141
	ds_read2_b32 v[224:225], v226 offset0:16 offset1:18
	s_waitcnt lgkmcnt(11)
	v_fmac_f32_e32 v230, v168, v142
	v_fmac_f32_e32 v231, v169, v143
	v_add_u32_e32 v227, 0x1400, v45
	ds_read2_b32 v[168:169], v227 offset0:0 offset1:2
	s_waitcnt lgkmcnt(11)
	v_fmac_f32_e32 v230, v170, v144
	v_fmac_f32_e32 v231, v171, v145
	v_add_f32_e32 v230, v230, v231
	s_nop 1
	v_add_f32_dpp v232, v230, v230 quad_perm:[1,0,3,2] row_mask:0xf bank_mask:0xf
	v_sub_f32_e32 v233, v145, v232
	v_cndmask_b32_e64 v145, v145, v233, s[4:5]
	ds_read2_b32 v[170:171], v227 offset0:4 offset1:6
	s_waitcnt lgkmcnt(11)
	v_mul_f32_e32 v230, v172, v136
	v_mul_f32_e32 v231, v173, v137
	ds_read2_b32 v[172:173], v227 offset0:8 offset1:10
	s_waitcnt lgkmcnt(11)
	v_fmac_f32_e32 v230, v174, v138
	v_fmac_f32_e32 v231, v175, v139
	ds_read2_b32 v[174:175], v227 offset0:12 offset1:14
	s_waitcnt lgkmcnt(11)
	v_fmac_f32_e32 v230, v176, v140
	v_fmac_f32_e32 v231, v177, v141
	ds_read2_b32 v[176:177], v227 offset0:16 offset1:18
	s_waitcnt lgkmcnt(11)
	v_fmac_f32_e32 v230, v178, v142
	v_fmac_f32_e32 v231, v179, v143
	ds_read2_b32 v[178:179], v227 offset0:20 offset1:22
	s_waitcnt lgkmcnt(11)
	v_fmac_f32_e32 v230, v180, v144
	v_fmac_f32_e32 v231, v181, v145
	v_add_f32_e32 v230, v230, v231
	s_nop 1
	v_add_f32_dpp v232, v230, v230 quad_perm:[1,0,3,2] row_mask:0xf bank_mask:0xf
	v_sub_f32_e32 v233, v145, v232
	v_cndmask_b32_e64 v145, v145, v233, s[8:9]
	v_add_u32_e32 v228, 0x1500, v45
	ds_read2_b32 v[180:181], v228 offset0:0 offset1:2
	s_waitcnt lgkmcnt(11)
	v_mul_f32_e32 v230, v210, v136
	v_mul_f32_e32 v231, v211, v137
	ds_read2_b32 v[210:211], v228 offset0:4 offset1:6
	s_waitcnt lgkmcnt(11)
	v_fmac_f32_e32 v230, v212, v138
	v_fmac_f32_e32 v231, v213, v139
	ds_read2_b32 v[212:213], v228 offset0:8 offset1:10
	s_waitcnt lgkmcnt(11)
	v_fmac_f32_e32 v230, v214, v140
	v_fmac_f32_e32 v231, v215, v141
	ds_read2_b32 v[214:215], v228 offset0:12 offset1:14
	s_waitcnt lgkmcnt(11)
	v_fmac_f32_e32 v230, v216, v142
	v_fmac_f32_e32 v231, v217, v143
	ds_read2_b32 v[216:217], v228 offset0:16 offset1:18
	s_waitcnt lgkmcnt(11)
	v_fmac_f32_e32 v230, v224, v144
	v_fmac_f32_e32 v231, v225, v145
	v_add_f32_e32 v230, v230, v231
	s_nop 1
	v_add_f32_dpp v232, v230, v230 quad_perm:[1,0,3,2] row_mask:0xf bank_mask:0xf
	v_sub_f32_e32 v233, v146, v232
	v_cndmask_b32_e64 v146, v146, v233, s[4:5]
	ds_read2_b32 v[224:225], v228 offset0:20 offset1:22
	s_waitcnt lgkmcnt(11)
	v_mul_f32_e32 v230, v168, v136
	v_mul_f32_e32 v231, v169, v137
	v_add_u32_e32 v229, 0x1600, v45
	ds_read2_b32 v[168:169], v229 offset0:0 offset1:2
	s_waitcnt lgkmcnt(11)
	v_fmac_f32_e32 v230, v170, v138
	v_fmac_f32_e32 v231, v171, v139
	ds_read2_b32 v[170:171], v229 offset0:4 offset1:6
	s_waitcnt lgkmcnt(11)
	v_fmac_f32_e32 v230, v172, v140
	v_fmac_f32_e32 v231, v173, v141
	ds_read2_b32 v[172:173], v229 offset0:8 offset1:10
	s_waitcnt lgkmcnt(11)
	v_fmac_f32_e32 v230, v174, v142
	v_fmac_f32_e32 v231, v175, v143
	ds_read2_b32 v[174:175], v229 offset0:12 offset1:14
	s_waitcnt lgkmcnt(11)
	v_fmac_f32_e32 v230, v176, v144
	v_fmac_f32_e32 v231, v177, v145
	ds_read2_b32 v[176:177], v229 offset0:16 offset1:18
	s_waitcnt lgkmcnt(11)
	v_fmac_f32_e32 v230, v178, v146
	v_fmac_f32_e32 v231, v179, v147
	v_add_f32_e32 v230, v230, v231
	s_nop 1
	v_add_f32_dpp v232, v230, v230 quad_perm:[1,0,3,2] row_mask:0xf bank_mask:0xf
	v_sub_f32_e32 v233, v146, v232
	v_cndmask_b32_e64 v146, v146, v233, s[8:9]
	ds_read2_b32 v[178:179], v229 offset0:20 offset1:22
	s_waitcnt lgkmcnt(11)
	v_mul_f32_e32 v230, v180, v136
	v_mul_f32_e32 v231, v181, v137
	v_add_u32_e32 v226, 0x1700, v45
	ds_read2_b32 v[180:181], v226 offset0:0 offset1:2
	s_waitcnt lgkmcnt(11)
	v_fmac_f32_e32 v230, v210, v138
	v_fmac_f32_e32 v231, v211, v139
	ds_read2_b32 v[210:211], v226 offset0:4 offset1:6
	s_waitcnt lgkmcnt(11)
	v_fmac_f32_e32 v230, v212, v140
	v_fmac_f32_e32 v231, v213, v141
	ds_read2_b32 v[212:213], v226 offset0:8 offset1:10
	s_waitcnt lgkmcnt(11)
	v_fmac_f32_e32 v230, v214, v142
	v_fmac_f32_e32 v231, v215, v143
	ds_read2_b32 v[214:215], v226 offset0:12 offset1:14
	s_waitcnt lgkmcnt(11)
	v_fmac_f32_e32 v230, v216, v144
	v_fmac_f32_e32 v231, v217, v145
	ds_read2_b32 v[216:217], v226 offset0:16 offset1:18
	s_waitcnt lgkmcnt(11)
	v_fmac_f32_e32 v230, v224, v146
	v_fmac_f32_e32 v231, v225, v147
	v_add_f32_e32 v230, v230, v231
	s_nop 1
	v_add_f32_dpp v232, v230, v230 quad_perm:[1,0,3,2] row_mask:0xf bank_mask:0xf
	v_sub_f32_e32 v233, v147, v232
	v_cndmask_b32_e64 v147, v147, v233, s[4:5]
	ds_read2_b32 v[224:225], v226 offset0:20 offset1:22
	s_waitcnt lgkmcnt(11)
	v_mul_f32_e32 v230, v168, v136
	v_mul_f32_e32 v231, v169, v137
	v_add_u32_e32 v227, 0x1800, v45
	ds_read2_b32 v[168:169], v227 offset0:0 offset1:2
	s_waitcnt lgkmcnt(11)
	v_fmac_f32_e32 v230, v170, v138
	v_fmac_f32_e32 v231, v171, v139
	ds_read2_b32 v[170:171], v227 offset0:4 offset1:6
	s_waitcnt lgkmcnt(11)
	v_fmac_f32_e32 v230, v172, v140
	v_fmac_f32_e32 v231, v173, v141
	ds_read2_b32 v[172:173], v227 offset0:8 offset1:10
	s_waitcnt lgkmcnt(11)
	v_fmac_f32_e32 v230, v174, v142
	v_fmac_f32_e32 v231, v175, v143
	ds_read2_b32 v[174:175], v227 offset0:12 offset1:14
	s_waitcnt lgkmcnt(11)
	v_fmac_f32_e32 v230, v176, v144
	v_fmac_f32_e32 v231, v177, v145
	ds_read2_b32 v[176:177], v227 offset0:16 offset1:18
	s_waitcnt lgkmcnt(11)
	v_fmac_f32_e32 v230, v178, v146
	v_fmac_f32_e32 v231, v179, v147
	v_add_f32_e32 v230, v230, v231
	s_nop 1
	v_add_f32_dpp v232, v230, v230 quad_perm:[1,0,3,2] row_mask:0xf bank_mask:0xf
	v_sub_f32_e32 v233, v147, v232
	v_cndmask_b32_e64 v147, v147, v233, s[8:9]
	ds_read2_b32 v[178:179], v227 offset0:20 offset1:22
	s_waitcnt lgkmcnt(11)
	v_mul_f32_e32 v230, v180, v136
	v_mul_f32_e32 v231, v181, v137
	ds_read2_b32 v[180:181], v227 offset0:24 offset1:26
	s_waitcnt lgkmcnt(11)
	v_fmac_f32_e32 v230, v210, v138
	v_fmac_f32_e32 v231, v211, v139
	v_add_u32_e32 v228, 0x1900, v45
	ds_read2_b32 v[210:211], v228 offset0:0 offset1:2
	s_waitcnt lgkmcnt(11)
	v_fmac_f32_e32 v230, v212, v140
	v_fmac_f32_e32 v231, v213, v141
	ds_read2_b32 v[212:213], v228 offset0:4 offset1:6
	s_waitcnt lgkmcnt(11)
	v_fmac_f32_e32 v230, v214, v142
	v_fmac_f32_e32 v231, v215, v143
	ds_read2_b32 v[214:215], v228 offset0:8 offset1:10
	s_waitcnt lgkmcnt(11)
	v_fmac_f32_e32 v230, v216, v144
	v_fmac_f32_e32 v231, v217, v145
	ds_read2_b32 v[216:217], v228 offset0:12 offset1:14
	s_waitcnt lgkmcnt(11)
	v_fmac_f32_e32 v230, v224, v146
	v_fmac_f32_e32 v231, v225, v147
	v_add_f32_e32 v230, v230, v231
	s_nop 1
	v_add_f32_dpp v232, v230, v230 quad_perm:[1,0,3,2] row_mask:0xf bank_mask:0xf
	v_sub_f32_e32 v233, v148, v232
	v_cndmask_b32_e64 v148, v148, v233, s[4:5]
	ds_read2_b32 v[224:225], v228 offset0:16 offset1:18
	s_waitcnt lgkmcnt(11)
	v_mul_f32_e32 v230, v168, v136
	v_mul_f32_e32 v231, v169, v137
	ds_read2_b32 v[168:169], v228 offset0:20 offset1:22
	s_waitcnt lgkmcnt(11)
	v_fmac_f32_e32 v230, v170, v138
	v_fmac_f32_e32 v231, v171, v139
	ds_read2_b32 v[170:171], v228 offset0:24 offset1:26
	s_waitcnt lgkmcnt(11)
	v_fmac_f32_e32 v230, v172, v140
	v_fmac_f32_e32 v231, v173, v141
	v_add_u32_e32 v229, 0x1a00, v45
	ds_read2_b32 v[172:173], v229 offset0:0 offset1:2
	s_waitcnt lgkmcnt(11)
	v_fmac_f32_e32 v230, v174, v142
	v_fmac_f32_e32 v231, v175, v143
	ds_read2_b32 v[174:175], v229 offset0:4 offset1:6
	s_waitcnt lgkmcnt(11)
	v_fmac_f32_e32 v230, v176, v144
	v_fmac_f32_e32 v231, v177, v145
	ds_read2_b32 v[176:177], v229 offset0:8 offset1:10
	s_waitcnt lgkmcnt(11)
	v_fmac_f32_e32 v230, v178, v146
	v_fmac_f32_e32 v231, v179, v147
	ds_read2_b32 v[178:179], v229 offset0:12 offset1:14
	s_waitcnt lgkmcnt(11)
	v_fmac_f32_e32 v230, v180, v148
	v_fmac_f32_e32 v231, v181, v149
	v_add_f32_e32 v230, v230, v231
	s_nop 1
	v_add_f32_dpp v232, v230, v230 quad_perm:[1,0,3,2] row_mask:0xf bank_mask:0xf
	v_sub_f32_e32 v233, v148, v232
	v_cndmask_b32_e64 v148, v148, v233, s[8:9]
	ds_read2_b32 v[180:181], v229 offset0:16 offset1:18
	s_waitcnt lgkmcnt(11)
	v_mul_f32_e32 v230, v210, v136
	v_mul_f32_e32 v231, v211, v137
	ds_read2_b32 v[210:211], v229 offset0:20 offset1:22
	s_waitcnt lgkmcnt(11)
	v_fmac_f32_e32 v230, v212, v138
	v_fmac_f32_e32 v231, v213, v139
	ds_read2_b32 v[212:213], v229 offset0:24 offset1:26
	s_waitcnt lgkmcnt(11)
	v_fmac_f32_e32 v230, v214, v140
	v_fmac_f32_e32 v231, v215, v141
	v_add_u32_e32 v226, 0x1b00, v45
	ds_read2_b32 v[214:215], v226 offset0:0 offset1:2
	s_waitcnt lgkmcnt(11)
	v_fmac_f32_e32 v230, v216, v142
	v_fmac_f32_e32 v231, v217, v143
	ds_read2_b32 v[216:217], v226 offset0:4 offset1:6
	s_waitcnt lgkmcnt(11)
	v_fmac_f32_e32 v230, v224, v144
	v_fmac_f32_e32 v231, v225, v145
	ds_read2_b32 v[224:225], v226 offset0:8 offset1:10
	s_waitcnt lgkmcnt(11)
	v_fmac_f32_e32 v230, v168, v146
	v_fmac_f32_e32 v231, v169, v147
	ds_read2_b32 v[168:169], v226 offset0:12 offset1:14
	s_waitcnt lgkmcnt(11)
	v_fmac_f32_e32 v230, v170, v148
	v_fmac_f32_e32 v231, v171, v149
	v_add_f32_e32 v230, v230, v231
	s_nop 1
	v_add_f32_dpp v232, v230, v230 quad_perm:[1,0,3,2] row_mask:0xf bank_mask:0xf
	v_sub_f32_e32 v233, v149, v232
	v_cndmask_b32_e64 v149, v149, v233, s[4:5]
	ds_read2_b32 v[170:171], v226 offset0:16 offset1:18
	s_waitcnt lgkmcnt(11)
	v_mul_f32_e32 v230, v172, v136
	v_mul_f32_e32 v231, v173, v137
	ds_read2_b32 v[172:173], v226 offset0:20 offset1:22
	s_waitcnt lgkmcnt(11)
	v_fmac_f32_e32 v230, v174, v138
	v_fmac_f32_e32 v231, v175, v139
	ds_read2_b32 v[174:175], v226 offset0:24 offset1:26
	s_waitcnt lgkmcnt(11)
	v_fmac_f32_e32 v230, v176, v140
	v_fmac_f32_e32 v231, v177, v141
	v_add_u32_e32 v227, 0x1c00, v45
	ds_read2_b32 v[176:177], v227 offset0:0 offset1:2
	s_waitcnt lgkmcnt(11)
	v_fmac_f32_e32 v230, v178, v142
	v_fmac_f32_e32 v231, v179, v143
	ds_read2_b32 v[178:179], v227 offset0:4 offset1:6
	s_waitcnt lgkmcnt(11)
	v_fmac_f32_e32 v230, v180, v144
	v_fmac_f32_e32 v231, v181, v145
	ds_read2_b32 v[180:181], v227 offset0:8 offset1:10
	s_waitcnt lgkmcnt(11)
	v_fmac_f32_e32 v230, v210, v146
	v_fmac_f32_e32 v231, v211, v147
	ds_read2_b32 v[210:211], v227 offset0:12 offset1:14
	s_waitcnt lgkmcnt(11)
	v_fmac_f32_e32 v230, v212, v148
	v_fmac_f32_e32 v231, v213, v149
	v_add_f32_e32 v230, v230, v231
	s_nop 1
	v_add_f32_dpp v232, v230, v230 quad_perm:[1,0,3,2] row_mask:0xf bank_mask:0xf
	v_sub_f32_e32 v233, v149, v232
	v_cndmask_b32_e64 v149, v149, v233, s[8:9]
	ds_read2_b32 v[212:213], v227 offset0:16 offset1:18
	s_waitcnt lgkmcnt(11)
	v_mul_f32_e32 v230, v214, v136
	v_mul_f32_e32 v231, v215, v137
	ds_read2_b32 v[214:215], v227 offset0:20 offset1:22
	s_waitcnt lgkmcnt(11)
	v_fmac_f32_e32 v230, v216, v138
	v_fmac_f32_e32 v231, v217, v139
	ds_read2_b32 v[216:217], v227 offset0:24 offset1:26
	s_waitcnt lgkmcnt(11)
	v_fmac_f32_e32 v230, v224, v140
	v_fmac_f32_e32 v231, v225, v141
	ds_read2_b32 v[224:225], v227 offset0:28 offset1:30
	s_waitcnt lgkmcnt(11)
	v_fmac_f32_e32 v230, v168, v142
	v_fmac_f32_e32 v231, v169, v143
	v_add_u32_e32 v228, 0x1d00, v45
	ds_read2_b32 v[168:169], v228 offset0:0 offset1:2
	s_waitcnt lgkmcnt(11)
	v_fmac_f32_e32 v230, v170, v144
	v_fmac_f32_e32 v231, v171, v145
	ds_read2_b32 v[170:171], v228 offset0:4 offset1:6
	s_waitcnt lgkmcnt(11)
	v_fmac_f32_e32 v230, v172, v146
	v_fmac_f32_e32 v231, v173, v147
	ds_read2_b32 v[172:173], v228 offset0:8 offset1:10
	s_waitcnt lgkmcnt(11)
	v_fmac_f32_e32 v230, v174, v148
	v_fmac_f32_e32 v231, v175, v149
	v_add_f32_e32 v230, v230, v231
	s_nop 1
	v_add_f32_dpp v232, v230, v230 quad_perm:[1,0,3,2] row_mask:0xf bank_mask:0xf
	v_sub_f32_e32 v233, v150, v232
	v_cndmask_b32_e64 v150, v150, v233, s[4:5]
	ds_read2_b32 v[174:175], v228 offset0:12 offset1:14
	s_waitcnt lgkmcnt(11)
	v_mul_f32_e32 v230, v176, v136
	v_mul_f32_e32 v231, v177, v137
	ds_read2_b32 v[176:177], v228 offset0:16 offset1:18
	s_waitcnt lgkmcnt(11)
	v_fmac_f32_e32 v230, v178, v138
	v_fmac_f32_e32 v231, v179, v139
	ds_read2_b32 v[178:179], v228 offset0:20 offset1:22
	s_waitcnt lgkmcnt(11)
	v_fmac_f32_e32 v230, v180, v140
	v_fmac_f32_e32 v231, v181, v141
	ds_read2_b32 v[180:181], v228 offset0:24 offset1:26
	s_waitcnt lgkmcnt(11)
	v_fmac_f32_e32 v230, v210, v142
	v_fmac_f32_e32 v231, v211, v143
	ds_read2_b32 v[210:211], v228 offset0:28 offset1:30
	s_waitcnt lgkmcnt(11)
	v_fmac_f32_e32 v230, v212, v144
	v_fmac_f32_e32 v231, v213, v145
	v_add_u32_e32 v229, 0x1e00, v45
	ds_read2_b32 v[212:213], v229 offset0:0 offset1:2
	s_waitcnt lgkmcnt(11)
	v_fmac_f32_e32 v230, v214, v146
	v_fmac_f32_e32 v231, v215, v147
	ds_read2_b32 v[214:215], v229 offset0:4 offset1:6
	s_waitcnt lgkmcnt(11)
	v_fmac_f32_e32 v230, v216, v148
	v_fmac_f32_e32 v231, v217, v149
	ds_read2_b32 v[216:217], v229 offset0:8 offset1:10
	s_waitcnt lgkmcnt(11)
	v_fmac_f32_e32 v230, v224, v150
	v_fmac_f32_e32 v231, v225, v151
	v_add_f32_e32 v230, v230, v231
	s_nop 1
	v_add_f32_dpp v232, v230, v230 quad_perm:[1,0,3,2] row_mask:0xf bank_mask:0xf
	v_sub_f32_e32 v233, v150, v232
	v_cndmask_b32_e64 v150, v150, v233, s[8:9]
	ds_read2_b32 v[224:225], v229 offset0:12 offset1:14
	s_waitcnt lgkmcnt(11)
	v_mul_f32_e32 v230, v168, v136
	v_mul_f32_e32 v231, v169, v137
	ds_read2_b32 v[168:169], v229 offset0:16 offset1:18
	s_waitcnt lgkmcnt(11)
	v_fmac_f32_e32 v230, v170, v138
	v_fmac_f32_e32 v231, v171, v139
	ds_read2_b32 v[170:171], v229 offset0:20 offset1:22
	s_waitcnt lgkmcnt(11)
	v_fmac_f32_e32 v230, v172, v140
	v_fmac_f32_e32 v231, v173, v141
	ds_read2_b32 v[172:173], v229 offset0:24 offset1:26
	s_waitcnt lgkmcnt(11)
	v_fmac_f32_e32 v230, v174, v142
	v_fmac_f32_e32 v231, v175, v143
	ds_read2_b32 v[174:175], v229 offset0:28 offset1:30
	s_waitcnt lgkmcnt(11)
	v_fmac_f32_e32 v230, v176, v144
	v_fmac_f32_e32 v231, v177, v145
	v_add_u32_e32 v226, 0x1f00, v45
	ds_read2_b32 v[176:177], v226 offset0:0 offset1:2
	s_waitcnt lgkmcnt(11)
	v_fmac_f32_e32 v230, v178, v146
	v_fmac_f32_e32 v231, v179, v147
	ds_read2_b32 v[178:179], v226 offset0:4 offset1:6
	s_waitcnt lgkmcnt(11)
	v_fmac_f32_e32 v230, v180, v148
	v_fmac_f32_e32 v231, v181, v149
	ds_read2_b32 v[180:181], v226 offset0:8 offset1:10
	s_waitcnt lgkmcnt(11)
	v_fmac_f32_e32 v230, v210, v150
	v_fmac_f32_e32 v231, v211, v151
	v_add_f32_e32 v230, v230, v231
	s_nop 1
	v_add_f32_dpp v232, v230, v230 quad_perm:[1,0,3,2] row_mask:0xf bank_mask:0xf
	v_sub_f32_e32 v233, v151, v232
	v_cndmask_b32_e64 v151, v151, v233, s[4:5]
	ds_read2_b32 v[210:211], v226 offset0:12 offset1:14
	s_waitcnt lgkmcnt(11)
	v_mul_f32_e32 v230, v212, v136
	v_mul_f32_e32 v231, v213, v137
	ds_read2_b32 v[212:213], v226 offset0:16 offset1:18
	s_waitcnt lgkmcnt(11)
	v_fmac_f32_e32 v230, v214, v138
	v_fmac_f32_e32 v231, v215, v139
	ds_read2_b32 v[214:215], v226 offset0:20 offset1:22
	s_waitcnt lgkmcnt(11)
	v_fmac_f32_e32 v230, v216, v140
	v_fmac_f32_e32 v231, v217, v141
	ds_read2_b32 v[216:217], v226 offset0:24 offset1:26
	s_waitcnt lgkmcnt(11)
	v_fmac_f32_e32 v230, v224, v142
	v_fmac_f32_e32 v231, v225, v143
	ds_read2_b32 v[224:225], v226 offset0:28 offset1:30
	s_waitcnt lgkmcnt(11)
	v_fmac_f32_e32 v230, v168, v144
	v_fmac_f32_e32 v231, v169, v145
	v_add_u32_e32 v227, 0x2000, v45
	ds_read2_b32 v[168:169], v227 offset0:0 offset1:2
	s_waitcnt lgkmcnt(11)
	v_fmac_f32_e32 v230, v170, v146
	v_fmac_f32_e32 v231, v171, v147
	ds_read2_b32 v[170:171], v227 offset0:4 offset1:6
	s_waitcnt lgkmcnt(11)
	v_fmac_f32_e32 v230, v172, v148
	v_fmac_f32_e32 v231, v173, v149
	ds_read2_b32 v[172:173], v227 offset0:8 offset1:10
	s_waitcnt lgkmcnt(11)
	v_fmac_f32_e32 v230, v174, v150
	v_fmac_f32_e32 v231, v175, v151
	v_add_f32_e32 v230, v230, v231
	s_nop 1
	v_add_f32_dpp v232, v230, v230 quad_perm:[1,0,3,2] row_mask:0xf bank_mask:0xf
	v_sub_f32_e32 v233, v151, v232
	v_cndmask_b32_e64 v151, v151, v233, s[8:9]
	ds_read2_b32 v[174:175], v227 offset0:12 offset1:14
	s_waitcnt lgkmcnt(11)
	v_mul_f32_e32 v230, v176, v136
	v_mul_f32_e32 v231, v177, v137
	ds_read2_b32 v[176:177], v227 offset0:16 offset1:18
	s_waitcnt lgkmcnt(11)
	v_fmac_f32_e32 v230, v178, v138
	v_fmac_f32_e32 v231, v179, v139
	ds_read2_b32 v[178:179], v227 offset0:20 offset1:22
	s_waitcnt lgkmcnt(11)
	v_fmac_f32_e32 v230, v180, v140
	v_fmac_f32_e32 v231, v181, v141
	ds_read2_b32 v[180:181], v227 offset0:24 offset1:26
	s_waitcnt lgkmcnt(11)
	v_fmac_f32_e32 v230, v210, v142
	v_fmac_f32_e32 v231, v211, v143
	ds_read2_b32 v[210:211], v227 offset0:28 offset1:30
	s_waitcnt lgkmcnt(11)
	v_fmac_f32_e32 v230, v212, v144
	v_fmac_f32_e32 v231, v213, v145
	ds_read2_b32 v[212:213], v227 offset0:32 offset1:34
	s_waitcnt lgkmcnt(11)
	v_fmac_f32_e32 v230, v214, v146
	v_fmac_f32_e32 v231, v215, v147
	v_add_u32_e32 v228, 0x2100, v45
	ds_read2_b32 v[214:215], v228 offset0:0 offset1:2
	s_waitcnt lgkmcnt(11)
	v_fmac_f32_e32 v230, v216, v148
	v_fmac_f32_e32 v231, v217, v149
	ds_read2_b32 v[216:217], v228 offset0:4 offset1:6
	s_waitcnt lgkmcnt(11)
	v_fmac_f32_e32 v230, v224, v150
	v_fmac_f32_e32 v231, v225, v151
	v_add_f32_e32 v230, v230, v231
	s_nop 1
	v_add_f32_dpp v232, v230, v230 quad_perm:[1,0,3,2] row_mask:0xf bank_mask:0xf
	v_sub_f32_e32 v233, v152, v232
	v_cndmask_b32_e64 v152, v152, v233, s[4:5]
	ds_read2_b32 v[224:225], v228 offset0:8 offset1:10
	s_waitcnt lgkmcnt(11)
	v_mul_f32_e32 v230, v168, v136
	v_mul_f32_e32 v231, v169, v137
	ds_read2_b32 v[168:169], v228 offset0:12 offset1:14
	s_waitcnt lgkmcnt(11)
	v_fmac_f32_e32 v230, v170, v138
	v_fmac_f32_e32 v231, v171, v139
	ds_read2_b32 v[170:171], v228 offset0:16 offset1:18
	s_waitcnt lgkmcnt(11)
	v_fmac_f32_e32 v230, v172, v140
	v_fmac_f32_e32 v231, v173, v141
	ds_read2_b32 v[172:173], v228 offset0:20 offset1:22
	s_waitcnt lgkmcnt(11)
	v_fmac_f32_e32 v230, v174, v142
	v_fmac_f32_e32 v231, v175, v143
	ds_read2_b32 v[174:175], v228 offset0:24 offset1:26
	s_waitcnt lgkmcnt(11)
	v_fmac_f32_e32 v230, v176, v144
	v_fmac_f32_e32 v231, v177, v145
	ds_read2_b32 v[176:177], v228 offset0:28 offset1:30
	s_waitcnt lgkmcnt(11)
	v_fmac_f32_e32 v230, v178, v146
	v_fmac_f32_e32 v231, v179, v147
	ds_read2_b32 v[178:179], v228 offset0:32 offset1:34
	s_waitcnt lgkmcnt(11)
	v_fmac_f32_e32 v230, v180, v148
	v_fmac_f32_e32 v231, v181, v149
	v_add_u32_e32 v229, 0x2200, v45
	ds_read2_b32 v[180:181], v229 offset0:0 offset1:2
	s_waitcnt lgkmcnt(11)
	v_fmac_f32_e32 v230, v210, v150
	v_fmac_f32_e32 v231, v211, v151
	ds_read2_b32 v[210:211], v229 offset0:4 offset1:6
	s_waitcnt lgkmcnt(11)
	v_fmac_f32_e32 v230, v212, v152
	v_fmac_f32_e32 v231, v213, v153
	v_add_f32_e32 v230, v230, v231
	s_nop 1
	v_add_f32_dpp v232, v230, v230 quad_perm:[1,0,3,2] row_mask:0xf bank_mask:0xf
	v_sub_f32_e32 v233, v152, v232
	v_cndmask_b32_e64 v152, v152, v233, s[8:9]
	ds_read2_b32 v[212:213], v229 offset0:8 offset1:10
	s_waitcnt lgkmcnt(11)
	v_mul_f32_e32 v230, v214, v136
	v_mul_f32_e32 v231, v215, v137
	ds_read2_b32 v[214:215], v229 offset0:12 offset1:14
	s_waitcnt lgkmcnt(11)
	v_fmac_f32_e32 v230, v216, v138
	v_fmac_f32_e32 v231, v217, v139
	ds_read2_b32 v[216:217], v229 offset0:16 offset1:18
	s_waitcnt lgkmcnt(11)
	v_fmac_f32_e32 v230, v224, v140
	v_fmac_f32_e32 v231, v225, v141
	ds_read2_b32 v[224:225], v229 offset0:20 offset1:22
	s_waitcnt lgkmcnt(11)
	v_fmac_f32_e32 v230, v168, v142
	v_fmac_f32_e32 v231, v169, v143
	ds_read2_b32 v[168:169], v229 offset0:24 offset1:26
	s_waitcnt lgkmcnt(11)
	v_fmac_f32_e32 v230, v170, v144
	v_fmac_f32_e32 v231, v171, v145
	ds_read2_b32 v[170:171], v229 offset0:28 offset1:30
	s_waitcnt lgkmcnt(11)
	v_fmac_f32_e32 v230, v172, v146
	v_fmac_f32_e32 v231, v173, v147
	ds_read2_b32 v[172:173], v229 offset0:32 offset1:34
	s_waitcnt lgkmcnt(11)
	v_fmac_f32_e32 v230, v174, v148
	v_fmac_f32_e32 v231, v175, v149
	v_add_u32_e32 v226, 0x2300, v45
	ds_read2_b32 v[174:175], v226 offset0:0 offset1:2
	s_waitcnt lgkmcnt(11)
	v_fmac_f32_e32 v230, v176, v150
	v_fmac_f32_e32 v231, v177, v151
	ds_read2_b32 v[176:177], v226 offset0:4 offset1:6
	s_waitcnt lgkmcnt(11)
	v_fmac_f32_e32 v230, v178, v152
	v_fmac_f32_e32 v231, v179, v153
	v_add_f32_e32 v230, v230, v231
	s_nop 1
	v_add_f32_dpp v232, v230, v230 quad_perm:[1,0,3,2] row_mask:0xf bank_mask:0xf
	v_sub_f32_e32 v233, v153, v232
	v_cndmask_b32_e64 v153, v153, v233, s[4:5]
	ds_read2_b32 v[178:179], v226 offset0:8 offset1:10
	s_waitcnt lgkmcnt(11)
	v_mul_f32_e32 v230, v180, v136
	v_mul_f32_e32 v231, v181, v137
	ds_read2_b32 v[180:181], v226 offset0:12 offset1:14
	s_waitcnt lgkmcnt(11)
	v_fmac_f32_e32 v230, v210, v138
	v_fmac_f32_e32 v231, v211, v139
	ds_read2_b32 v[210:211], v226 offset0:16 offset1:18
	s_waitcnt lgkmcnt(11)
	v_fmac_f32_e32 v230, v212, v140
	v_fmac_f32_e32 v231, v213, v141
	ds_read2_b32 v[212:213], v226 offset0:20 offset1:22
	s_waitcnt lgkmcnt(11)
	v_fmac_f32_e32 v230, v214, v142
	v_fmac_f32_e32 v231, v215, v143
	ds_read2_b32 v[214:215], v226 offset0:24 offset1:26
	s_waitcnt lgkmcnt(11)
	v_fmac_f32_e32 v230, v216, v144
	v_fmac_f32_e32 v231, v217, v145
	ds_read2_b32 v[216:217], v226 offset0:28 offset1:30
	s_waitcnt lgkmcnt(11)
	v_fmac_f32_e32 v230, v224, v146
	v_fmac_f32_e32 v231, v225, v147
	ds_read2_b32 v[224:225], v226 offset0:32 offset1:34
	s_waitcnt lgkmcnt(11)
	v_fmac_f32_e32 v230, v168, v148
	v_fmac_f32_e32 v231, v169, v149
	v_add_u32_e32 v227, 0x2400, v45
	ds_read2_b32 v[168:169], v227 offset0:0 offset1:2
	s_waitcnt lgkmcnt(11)
	v_fmac_f32_e32 v230, v170, v150
	v_fmac_f32_e32 v231, v171, v151
	ds_read2_b32 v[170:171], v227 offset0:4 offset1:6
	s_waitcnt lgkmcnt(11)
	v_fmac_f32_e32 v230, v172, v152
	v_fmac_f32_e32 v231, v173, v153
	v_add_f32_e32 v230, v230, v231
	s_nop 1
	v_add_f32_dpp v232, v230, v230 quad_perm:[1,0,3,2] row_mask:0xf bank_mask:0xf
	v_sub_f32_e32 v233, v153, v232
	v_cndmask_b32_e64 v153, v153, v233, s[8:9]
	ds_read2_b32 v[172:173], v227 offset0:8 offset1:10
	s_waitcnt lgkmcnt(11)
	v_mul_f32_e32 v230, v174, v136
	v_mul_f32_e32 v231, v175, v137
	ds_read2_b32 v[174:175], v227 offset0:12 offset1:14
	s_waitcnt lgkmcnt(11)
	v_fmac_f32_e32 v230, v176, v138
	v_fmac_f32_e32 v231, v177, v139
	ds_read2_b32 v[176:177], v227 offset0:16 offset1:18
	s_waitcnt lgkmcnt(11)
	v_fmac_f32_e32 v230, v178, v140
	v_fmac_f32_e32 v231, v179, v141
	ds_read2_b32 v[178:179], v227 offset0:20 offset1:22
	s_waitcnt lgkmcnt(11)
	v_fmac_f32_e32 v230, v180, v142
	v_fmac_f32_e32 v231, v181, v143
	ds_read2_b32 v[180:181], v227 offset0:24 offset1:26
	s_waitcnt lgkmcnt(11)
	v_fmac_f32_e32 v230, v210, v144
	v_fmac_f32_e32 v231, v211, v145
	ds_read2_b32 v[210:211], v227 offset0:28 offset1:30
	s_waitcnt lgkmcnt(11)
	v_fmac_f32_e32 v230, v212, v146
	v_fmac_f32_e32 v231, v213, v147
	ds_read2_b32 v[212:213], v227 offset0:32 offset1:34
	s_waitcnt lgkmcnt(11)
	v_fmac_f32_e32 v230, v214, v148
	v_fmac_f32_e32 v231, v215, v149
	ds_read2_b32 v[214:215], v227 offset0:36 offset1:38
	s_waitcnt lgkmcnt(11)
	v_fmac_f32_e32 v230, v216, v150
	v_fmac_f32_e32 v231, v217, v151
	v_add_u32_e32 v228, 0x2500, v45
	ds_read2_b32 v[216:217], v228 offset0:0 offset1:2
	s_waitcnt lgkmcnt(11)
	v_fmac_f32_e32 v230, v224, v152
	v_fmac_f32_e32 v231, v225, v153
	v_add_f32_e32 v230, v230, v231
	s_nop 1
	v_add_f32_dpp v232, v230, v230 quad_perm:[1,0,3,2] row_mask:0xf bank_mask:0xf
	v_sub_f32_e32 v233, v154, v232
	v_cndmask_b32_e64 v154, v154, v233, s[4:5]
	ds_read2_b32 v[224:225], v228 offset0:4 offset1:6
	s_waitcnt lgkmcnt(11)
	v_mul_f32_e32 v230, v168, v136
	v_mul_f32_e32 v231, v169, v137
	ds_read2_b32 v[168:169], v228 offset0:8 offset1:10
	s_waitcnt lgkmcnt(11)
	v_fmac_f32_e32 v230, v170, v138
	v_fmac_f32_e32 v231, v171, v139
	ds_read2_b32 v[170:171], v228 offset0:12 offset1:14
	s_waitcnt lgkmcnt(11)
	v_fmac_f32_e32 v230, v172, v140
	v_fmac_f32_e32 v231, v173, v141
	ds_read2_b32 v[172:173], v228 offset0:16 offset1:18
	s_waitcnt lgkmcnt(11)
	v_fmac_f32_e32 v230, v174, v142
	v_fmac_f32_e32 v231, v175, v143
	ds_read2_b32 v[174:175], v228 offset0:20 offset1:22
	s_waitcnt lgkmcnt(11)
	v_fmac_f32_e32 v230, v176, v144
	v_fmac_f32_e32 v231, v177, v145
	ds_read2_b32 v[176:177], v228 offset0:24 offset1:26
	s_waitcnt lgkmcnt(11)
	v_fmac_f32_e32 v230, v178, v146
	v_fmac_f32_e32 v231, v179, v147
	ds_read2_b32 v[178:179], v228 offset0:28 offset1:30
	s_waitcnt lgkmcnt(11)
	v_fmac_f32_e32 v230, v180, v148
	v_fmac_f32_e32 v231, v181, v149
	ds_read2_b32 v[180:181], v228 offset0:32 offset1:34
	s_waitcnt lgkmcnt(11)
	v_fmac_f32_e32 v230, v210, v150
	v_fmac_f32_e32 v231, v211, v151
	ds_read2_b32 v[210:211], v228 offset0:36 offset1:38
	s_waitcnt lgkmcnt(11)
	v_fmac_f32_e32 v230, v212, v152
	v_fmac_f32_e32 v231, v213, v153
	v_add_u32_e32 v229, 0x2600, v45
	ds_read2_b32 v[212:213], v229 offset0:0 offset1:2
	s_waitcnt lgkmcnt(11)
	v_fmac_f32_e32 v230, v214, v154
	v_fmac_f32_e32 v231, v215, v155
	v_add_f32_e32 v230, v230, v231
	s_nop 1
	v_add_f32_dpp v232, v230, v230 quad_perm:[1,0,3,2] row_mask:0xf bank_mask:0xf
	v_sub_f32_e32 v233, v154, v232
	v_cndmask_b32_e64 v154, v154, v233, s[8:9]
	ds_read2_b32 v[214:215], v229 offset0:4 offset1:6
	s_waitcnt lgkmcnt(11)
	v_mul_f32_e32 v230, v216, v136
	v_mul_f32_e32 v231, v217, v137
	ds_read2_b32 v[216:217], v229 offset0:8 offset1:10
	s_waitcnt lgkmcnt(11)
	v_fmac_f32_e32 v230, v224, v138
	v_fmac_f32_e32 v231, v225, v139
	ds_read2_b32 v[224:225], v229 offset0:12 offset1:14
	s_waitcnt lgkmcnt(11)
	v_fmac_f32_e32 v230, v168, v140
	v_fmac_f32_e32 v231, v169, v141
	ds_read2_b32 v[168:169], v229 offset0:16 offset1:18
	s_waitcnt lgkmcnt(11)
	v_fmac_f32_e32 v230, v170, v142
	v_fmac_f32_e32 v231, v171, v143
	ds_read2_b32 v[170:171], v229 offset0:20 offset1:22
	s_waitcnt lgkmcnt(11)
	v_fmac_f32_e32 v230, v172, v144
	v_fmac_f32_e32 v231, v173, v145
	ds_read2_b32 v[172:173], v229 offset0:24 offset1:26
	s_waitcnt lgkmcnt(11)
	v_fmac_f32_e32 v230, v174, v146
	v_fmac_f32_e32 v231, v175, v147
	ds_read2_b32 v[174:175], v229 offset0:28 offset1:30
	s_waitcnt lgkmcnt(11)
	v_fmac_f32_e32 v230, v176, v148
	v_fmac_f32_e32 v231, v177, v149
	ds_read2_b32 v[176:177], v229 offset0:32 offset1:34
	s_waitcnt lgkmcnt(11)
	v_fmac_f32_e32 v230, v178, v150
	v_fmac_f32_e32 v231, v179, v151
	ds_read2_b32 v[178:179], v229 offset0:36 offset1:38
	s_waitcnt lgkmcnt(11)
	v_fmac_f32_e32 v230, v180, v152
	v_fmac_f32_e32 v231, v181, v153
	v_add_u32_e32 v226, 0x2700, v45
	ds_read2_b32 v[180:181], v226 offset0:0 offset1:2
	s_waitcnt lgkmcnt(11)
	v_fmac_f32_e32 v230, v210, v154
	v_fmac_f32_e32 v231, v211, v155
	v_add_f32_e32 v230, v230, v231
	s_nop 1
	v_add_f32_dpp v232, v230, v230 quad_perm:[1,0,3,2] row_mask:0xf bank_mask:0xf
	v_sub_f32_e32 v233, v155, v232
	v_cndmask_b32_e64 v155, v155, v233, s[4:5]
	ds_read2_b32 v[210:211], v226 offset0:4 offset1:6
	s_waitcnt lgkmcnt(11)
	v_mul_f32_e32 v230, v212, v136
	v_mul_f32_e32 v231, v213, v137
	ds_read2_b32 v[212:213], v226 offset0:8 offset1:10
	s_waitcnt lgkmcnt(11)
	v_fmac_f32_e32 v230, v214, v138
	v_fmac_f32_e32 v231, v215, v139
	ds_read2_b32 v[214:215], v226 offset0:12 offset1:14
	s_waitcnt lgkmcnt(11)
	v_fmac_f32_e32 v230, v216, v140
	v_fmac_f32_e32 v231, v217, v141
	ds_read2_b32 v[216:217], v226 offset0:16 offset1:18
	s_waitcnt lgkmcnt(11)
	v_fmac_f32_e32 v230, v224, v142
	v_fmac_f32_e32 v231, v225, v143
	ds_read2_b32 v[224:225], v226 offset0:20 offset1:22
	s_waitcnt lgkmcnt(11)
	v_fmac_f32_e32 v230, v168, v144
	v_fmac_f32_e32 v231, v169, v145
	ds_read2_b32 v[168:169], v226 offset0:24 offset1:26
	s_waitcnt lgkmcnt(11)
	v_fmac_f32_e32 v230, v170, v146
	v_fmac_f32_e32 v231, v171, v147
	ds_read2_b32 v[170:171], v226 offset0:28 offset1:30
	s_waitcnt lgkmcnt(11)
	v_fmac_f32_e32 v230, v172, v148
	v_fmac_f32_e32 v231, v173, v149
	ds_read2_b32 v[172:173], v226 offset0:32 offset1:34
	s_waitcnt lgkmcnt(11)
	v_fmac_f32_e32 v230, v174, v150
	v_fmac_f32_e32 v231, v175, v151
	ds_read2_b32 v[174:175], v226 offset0:36 offset1:38
	s_waitcnt lgkmcnt(11)
	v_fmac_f32_e32 v230, v176, v152
	v_fmac_f32_e32 v231, v177, v153
	v_add_u32_e32 v227, 0x2800, v45
	ds_read2_b32 v[176:177], v227 offset0:0 offset1:2
	s_waitcnt lgkmcnt(11)
	v_fmac_f32_e32 v230, v178, v154
	v_fmac_f32_e32 v231, v179, v155
	v_add_f32_e32 v230, v230, v231
	s_nop 1
	v_add_f32_dpp v232, v230, v230 quad_perm:[1,0,3,2] row_mask:0xf bank_mask:0xf
	v_sub_f32_e32 v233, v155, v232
	v_cndmask_b32_e64 v155, v155, v233, s[8:9]
	ds_read2_b32 v[178:179], v227 offset0:4 offset1:6
	s_waitcnt lgkmcnt(11)
	v_mul_f32_e32 v230, v180, v136
	v_mul_f32_e32 v231, v181, v137
	ds_read2_b32 v[180:181], v227 offset0:8 offset1:10
	s_waitcnt lgkmcnt(11)
	v_fmac_f32_e32 v230, v210, v138
	v_fmac_f32_e32 v231, v211, v139
	ds_read2_b32 v[210:211], v227 offset0:12 offset1:14
	s_waitcnt lgkmcnt(11)
	v_fmac_f32_e32 v230, v212, v140
	v_fmac_f32_e32 v231, v213, v141
	ds_read2_b32 v[212:213], v227 offset0:16 offset1:18
	s_waitcnt lgkmcnt(11)
	v_fmac_f32_e32 v230, v214, v142
	v_fmac_f32_e32 v231, v215, v143
	ds_read2_b32 v[214:215], v227 offset0:20 offset1:22
	s_waitcnt lgkmcnt(11)
	v_fmac_f32_e32 v230, v216, v144
	v_fmac_f32_e32 v231, v217, v145
	ds_read2_b32 v[216:217], v227 offset0:24 offset1:26
	s_waitcnt lgkmcnt(11)
	v_fmac_f32_e32 v230, v224, v146
	v_fmac_f32_e32 v231, v225, v147
	ds_read2_b32 v[224:225], v227 offset0:28 offset1:30
	s_waitcnt lgkmcnt(11)
	v_fmac_f32_e32 v230, v168, v148
	v_fmac_f32_e32 v231, v169, v149
	ds_read2_b32 v[168:169], v227 offset0:32 offset1:34
	s_waitcnt lgkmcnt(11)
	v_fmac_f32_e32 v230, v170, v150
	v_fmac_f32_e32 v231, v171, v151
	ds_read2_b32 v[170:171], v227 offset0:36 offset1:38
	s_waitcnt lgkmcnt(11)
	v_fmac_f32_e32 v230, v172, v152
	v_fmac_f32_e32 v231, v173, v153
	ds_read2_b32 v[172:173], v227 offset0:40 offset1:42
	s_waitcnt lgkmcnt(11)
	v_fmac_f32_e32 v230, v174, v154
	v_fmac_f32_e32 v231, v175, v155
	v_add_f32_e32 v230, v230, v231
	s_nop 1
	v_add_f32_dpp v232, v230, v230 quad_perm:[1,0,3,2] row_mask:0xf bank_mask:0xf
	v_sub_f32_e32 v233, v156, v232
	v_cndmask_b32_e64 v156, v156, v233, s[4:5]
	v_add_u32_e32 v228, 0x2900, v45
	ds_read2_b32 v[174:175], v228 offset0:0 offset1:2
	s_waitcnt lgkmcnt(11)
	v_mul_f32_e32 v230, v176, v136
	v_mul_f32_e32 v231, v177, v137
	ds_read2_b32 v[176:177], v228 offset0:4 offset1:6
	s_waitcnt lgkmcnt(11)
	v_fmac_f32_e32 v230, v178, v138
	v_fmac_f32_e32 v231, v179, v139
	ds_read2_b32 v[178:179], v228 offset0:8 offset1:10
	s_waitcnt lgkmcnt(11)
	v_fmac_f32_e32 v230, v180, v140
	v_fmac_f32_e32 v231, v181, v141
	ds_read2_b32 v[180:181], v228 offset0:12 offset1:14
	s_waitcnt lgkmcnt(11)
	v_fmac_f32_e32 v230, v210, v142
	v_fmac_f32_e32 v231, v211, v143
	ds_read2_b32 v[210:211], v228 offset0:16 offset1:18
	s_waitcnt lgkmcnt(11)
	v_fmac_f32_e32 v230, v212, v144
	v_fmac_f32_e32 v231, v213, v145
	ds_read2_b32 v[212:213], v228 offset0:20 offset1:22
	s_waitcnt lgkmcnt(11)
	v_fmac_f32_e32 v230, v214, v146
	v_fmac_f32_e32 v231, v215, v147
	ds_read2_b32 v[214:215], v228 offset0:24 offset1:26
	s_waitcnt lgkmcnt(11)
	v_fmac_f32_e32 v230, v216, v148
	v_fmac_f32_e32 v231, v217, v149
	ds_read2_b32 v[216:217], v228 offset0:28 offset1:30
	s_waitcnt lgkmcnt(11)
	v_fmac_f32_e32 v230, v224, v150
	v_fmac_f32_e32 v231, v225, v151
	ds_read2_b32 v[224:225], v228 offset0:32 offset1:34
	s_waitcnt lgkmcnt(11)
	v_fmac_f32_e32 v230, v168, v152
	v_fmac_f32_e32 v231, v169, v153
	ds_read2_b32 v[168:169], v228 offset0:36 offset1:38
	s_waitcnt lgkmcnt(11)
	v_fmac_f32_e32 v230, v170, v154
	v_fmac_f32_e32 v231, v171, v155
	ds_read2_b32 v[170:171], v228 offset0:40 offset1:42
	s_waitcnt lgkmcnt(11)
	v_fmac_f32_e32 v230, v172, v156
	v_fmac_f32_e32 v231, v173, v157
	v_add_f32_e32 v230, v230, v231
	s_nop 1
	v_add_f32_dpp v232, v230, v230 quad_perm:[1,0,3,2] row_mask:0xf bank_mask:0xf
	v_sub_f32_e32 v233, v156, v232
	v_cndmask_b32_e64 v156, v156, v233, s[8:9]
	v_add_u32_e32 v229, 0x2a00, v45
	ds_read2_b32 v[172:173], v229 offset0:0 offset1:2
	s_waitcnt lgkmcnt(11)
	v_mul_f32_e32 v230, v174, v136
	v_mul_f32_e32 v231, v175, v137
	ds_read2_b32 v[174:175], v229 offset0:4 offset1:6
	s_waitcnt lgkmcnt(11)
	v_fmac_f32_e32 v230, v176, v138
	v_fmac_f32_e32 v231, v177, v139
	ds_read2_b32 v[176:177], v229 offset0:8 offset1:10
	s_waitcnt lgkmcnt(11)
	v_fmac_f32_e32 v230, v178, v140
	v_fmac_f32_e32 v231, v179, v141
	ds_read2_b32 v[178:179], v229 offset0:12 offset1:14
	s_waitcnt lgkmcnt(11)
	v_fmac_f32_e32 v230, v180, v142
	v_fmac_f32_e32 v231, v181, v143
	ds_read2_b32 v[180:181], v229 offset0:16 offset1:18
	s_waitcnt lgkmcnt(11)
	v_fmac_f32_e32 v230, v210, v144
	v_fmac_f32_e32 v231, v211, v145
	ds_read2_b32 v[210:211], v229 offset0:20 offset1:22
	s_waitcnt lgkmcnt(11)
	v_fmac_f32_e32 v230, v212, v146
	v_fmac_f32_e32 v231, v213, v147
	ds_read2_b32 v[212:213], v229 offset0:24 offset1:26
	s_waitcnt lgkmcnt(11)
	v_fmac_f32_e32 v230, v214, v148
	v_fmac_f32_e32 v231, v215, v149
	ds_read2_b32 v[214:215], v229 offset0:28 offset1:30
	s_waitcnt lgkmcnt(11)
	v_fmac_f32_e32 v230, v216, v150
	v_fmac_f32_e32 v231, v217, v151
	ds_read2_b32 v[216:217], v229 offset0:32 offset1:34
	s_waitcnt lgkmcnt(11)
	v_fmac_f32_e32 v230, v224, v152
	v_fmac_f32_e32 v231, v225, v153
	ds_read2_b32 v[224:225], v229 offset0:36 offset1:38
	s_waitcnt lgkmcnt(11)
	v_fmac_f32_e32 v230, v168, v154
	v_fmac_f32_e32 v231, v169, v155
	ds_read2_b32 v[168:169], v229 offset0:40 offset1:42
	s_waitcnt lgkmcnt(11)
	v_fmac_f32_e32 v230, v170, v156
	v_fmac_f32_e32 v231, v171, v157
	v_add_f32_e32 v230, v230, v231
	s_nop 1
	v_add_f32_dpp v232, v230, v230 quad_perm:[1,0,3,2] row_mask:0xf bank_mask:0xf
	v_sub_f32_e32 v233, v157, v232
	v_cndmask_b32_e64 v157, v157, v233, s[4:5]
	v_add_u32_e32 v226, 0x2b00, v45
	ds_read2_b32 v[170:171], v226 offset0:0 offset1:2
	s_waitcnt lgkmcnt(11)
	v_mul_f32_e32 v230, v172, v136
	v_mul_f32_e32 v231, v173, v137
	ds_read2_b32 v[172:173], v226 offset0:4 offset1:6
	s_waitcnt lgkmcnt(11)
	v_fmac_f32_e32 v230, v174, v138
	v_fmac_f32_e32 v231, v175, v139
	ds_read2_b32 v[174:175], v226 offset0:8 offset1:10
	s_waitcnt lgkmcnt(11)
	v_fmac_f32_e32 v230, v176, v140
	v_fmac_f32_e32 v231, v177, v141
	ds_read2_b32 v[176:177], v226 offset0:12 offset1:14
	s_waitcnt lgkmcnt(11)
	v_fmac_f32_e32 v230, v178, v142
	v_fmac_f32_e32 v231, v179, v143
	ds_read2_b32 v[178:179], v226 offset0:16 offset1:18
	s_waitcnt lgkmcnt(11)
	v_fmac_f32_e32 v230, v180, v144
	v_fmac_f32_e32 v231, v181, v145
	ds_read2_b32 v[180:181], v226 offset0:20 offset1:22
	s_waitcnt lgkmcnt(11)
	v_fmac_f32_e32 v230, v210, v146
	v_fmac_f32_e32 v231, v211, v147
	ds_read2_b32 v[210:211], v226 offset0:24 offset1:26
	s_waitcnt lgkmcnt(11)
	v_fmac_f32_e32 v230, v212, v148
	v_fmac_f32_e32 v231, v213, v149
	ds_read2_b32 v[212:213], v226 offset0:28 offset1:30
	s_waitcnt lgkmcnt(11)
	v_fmac_f32_e32 v230, v214, v150
	v_fmac_f32_e32 v231, v215, v151
	ds_read2_b32 v[214:215], v226 offset0:32 offset1:34
	s_waitcnt lgkmcnt(11)
	v_fmac_f32_e32 v230, v216, v152
	v_fmac_f32_e32 v231, v217, v153
	ds_read2_b32 v[216:217], v226 offset0:36 offset1:38
	s_waitcnt lgkmcnt(11)
	v_fmac_f32_e32 v230, v224, v154
	v_fmac_f32_e32 v231, v225, v155
	ds_read2_b32 v[224:225], v226 offset0:40 offset1:42
	s_waitcnt lgkmcnt(11)
	v_fmac_f32_e32 v230, v168, v156
	v_fmac_f32_e32 v231, v169, v157
	v_add_f32_e32 v230, v230, v231
	s_nop 1
	v_add_f32_dpp v232, v230, v230 quad_perm:[1,0,3,2] row_mask:0xf bank_mask:0xf
	v_sub_f32_e32 v233, v157, v232
	v_cndmask_b32_e64 v157, v157, v233, s[8:9]
	v_add_u32_e32 v227, 0x2c00, v45
	ds_read2_b32 v[168:169], v227 offset0:0 offset1:2
	s_waitcnt lgkmcnt(11)
	v_mul_f32_e32 v230, v170, v136
	v_mul_f32_e32 v231, v171, v137
	ds_read2_b32 v[170:171], v227 offset0:4 offset1:6
	s_waitcnt lgkmcnt(11)
	v_fmac_f32_e32 v230, v172, v138
	v_fmac_f32_e32 v231, v173, v139
	ds_read2_b32 v[172:173], v227 offset0:8 offset1:10
	s_waitcnt lgkmcnt(11)
	v_fmac_f32_e32 v230, v174, v140
	v_fmac_f32_e32 v231, v175, v141
	ds_read2_b32 v[174:175], v227 offset0:12 offset1:14
	s_waitcnt lgkmcnt(11)
	v_fmac_f32_e32 v230, v176, v142
	v_fmac_f32_e32 v231, v177, v143
	ds_read2_b32 v[176:177], v227 offset0:16 offset1:18
	s_waitcnt lgkmcnt(11)
	v_fmac_f32_e32 v230, v178, v144
	v_fmac_f32_e32 v231, v179, v145
	ds_read2_b32 v[178:179], v227 offset0:20 offset1:22
	s_waitcnt lgkmcnt(11)
	v_fmac_f32_e32 v230, v180, v146
	v_fmac_f32_e32 v231, v181, v147
	ds_read2_b32 v[180:181], v227 offset0:24 offset1:26
	s_waitcnt lgkmcnt(11)
	v_fmac_f32_e32 v230, v210, v148
	v_fmac_f32_e32 v231, v211, v149
	ds_read2_b32 v[210:211], v227 offset0:28 offset1:30
	s_waitcnt lgkmcnt(11)
	v_fmac_f32_e32 v230, v212, v150
	v_fmac_f32_e32 v231, v213, v151
	ds_read2_b32 v[212:213], v227 offset0:32 offset1:34
	s_waitcnt lgkmcnt(11)
	v_fmac_f32_e32 v230, v214, v152
	v_fmac_f32_e32 v231, v215, v153
	ds_read2_b32 v[214:215], v227 offset0:36 offset1:38
	s_waitcnt lgkmcnt(11)
	v_fmac_f32_e32 v230, v216, v154
	v_fmac_f32_e32 v231, v217, v155
	ds_read2_b32 v[216:217], v227 offset0:40 offset1:42
	s_waitcnt lgkmcnt(11)
	v_fmac_f32_e32 v230, v224, v156
	v_fmac_f32_e32 v231, v225, v157
	v_add_f32_e32 v230, v230, v231
	s_nop 1
	v_add_f32_dpp v232, v230, v230 quad_perm:[1,0,3,2] row_mask:0xf bank_mask:0xf
	v_sub_f32_e32 v233, v158, v232
	v_cndmask_b32_e64 v158, v158, v233, s[4:5]
	ds_read2_b32 v[224:225], v227 offset0:44 offset1:46
	s_waitcnt lgkmcnt(11)
	v_mul_f32_e32 v230, v168, v136
	v_mul_f32_e32 v231, v169, v137
	v_add_u32_e32 v228, 0x2d00, v45
	ds_read2_b32 v[168:169], v228 offset0:0 offset1:2
	s_waitcnt lgkmcnt(11)
	v_fmac_f32_e32 v230, v170, v138
	v_fmac_f32_e32 v231, v171, v139
	ds_read2_b32 v[170:171], v228 offset0:4 offset1:6
	s_waitcnt lgkmcnt(11)
	v_fmac_f32_e32 v230, v172, v140
	v_fmac_f32_e32 v231, v173, v141
	ds_read2_b32 v[172:173], v228 offset0:8 offset1:10
	s_waitcnt lgkmcnt(11)
	v_fmac_f32_e32 v230, v174, v142
	v_fmac_f32_e32 v231, v175, v143
	ds_read2_b32 v[174:175], v228 offset0:12 offset1:14
	s_waitcnt lgkmcnt(11)
	v_fmac_f32_e32 v230, v176, v144
	v_fmac_f32_e32 v231, v177, v145
	ds_read2_b32 v[176:177], v228 offset0:16 offset1:18
	s_waitcnt lgkmcnt(11)
	v_fmac_f32_e32 v230, v178, v146
	v_fmac_f32_e32 v231, v179, v147
	ds_read2_b32 v[178:179], v228 offset0:20 offset1:22
	s_waitcnt lgkmcnt(11)
	v_fmac_f32_e32 v230, v180, v148
	v_fmac_f32_e32 v231, v181, v149
	ds_read2_b32 v[180:181], v228 offset0:24 offset1:26
	s_waitcnt lgkmcnt(11)
	v_fmac_f32_e32 v230, v210, v150
	v_fmac_f32_e32 v231, v211, v151
	ds_read2_b32 v[210:211], v228 offset0:28 offset1:30
	s_waitcnt lgkmcnt(11)
	v_fmac_f32_e32 v230, v212, v152
	v_fmac_f32_e32 v231, v213, v153
	ds_read2_b32 v[212:213], v228 offset0:32 offset1:34
	s_waitcnt lgkmcnt(11)
	v_fmac_f32_e32 v230, v214, v154
	v_fmac_f32_e32 v231, v215, v155
	ds_read2_b32 v[214:215], v228 offset0:36 offset1:38
	s_waitcnt lgkmcnt(11)
	v_fmac_f32_e32 v230, v216, v156
	v_fmac_f32_e32 v231, v217, v157
	ds_read2_b32 v[216:217], v228 offset0:40 offset1:42
	s_waitcnt lgkmcnt(11)
	v_fmac_f32_e32 v230, v224, v158
	v_fmac_f32_e32 v231, v225, v159
	v_add_f32_e32 v230, v230, v231
	s_nop 1
	v_add_f32_dpp v232, v230, v230 quad_perm:[1,0,3,2] row_mask:0xf bank_mask:0xf
	v_sub_f32_e32 v233, v158, v232
	v_cndmask_b32_e64 v158, v158, v233, s[8:9]
	ds_read2_b32 v[224:225], v228 offset0:44 offset1:46
	s_waitcnt lgkmcnt(11)
	v_mul_f32_e32 v230, v168, v136
	v_mul_f32_e32 v231, v169, v137
	v_add_u32_e32 v229, 0x2e00, v45
	ds_read2_b32 v[168:169], v229 offset0:0 offset1:2
	s_waitcnt lgkmcnt(11)
	v_fmac_f32_e32 v230, v170, v138
	v_fmac_f32_e32 v231, v171, v139
	ds_read2_b32 v[170:171], v229 offset0:4 offset1:6
	s_waitcnt lgkmcnt(11)
	v_fmac_f32_e32 v230, v172, v140
	v_fmac_f32_e32 v231, v173, v141
	ds_read2_b32 v[172:173], v229 offset0:8 offset1:10
	s_waitcnt lgkmcnt(11)
	v_fmac_f32_e32 v230, v174, v142
	v_fmac_f32_e32 v231, v175, v143
	ds_read2_b32 v[174:175], v229 offset0:12 offset1:14
	s_waitcnt lgkmcnt(11)
	v_fmac_f32_e32 v230, v176, v144
	v_fmac_f32_e32 v231, v177, v145
	ds_read2_b32 v[176:177], v229 offset0:16 offset1:18
	s_waitcnt lgkmcnt(11)
	v_fmac_f32_e32 v230, v178, v146
	v_fmac_f32_e32 v231, v179, v147
	ds_read2_b32 v[178:179], v229 offset0:20 offset1:22
	s_waitcnt lgkmcnt(11)
	v_fmac_f32_e32 v230, v180, v148
	v_fmac_f32_e32 v231, v181, v149
	ds_read2_b32 v[180:181], v229 offset0:24 offset1:26
	s_waitcnt lgkmcnt(11)
	v_fmac_f32_e32 v230, v210, v150
	v_fmac_f32_e32 v231, v211, v151
	ds_read2_b32 v[210:211], v229 offset0:28 offset1:30
	s_waitcnt lgkmcnt(11)
	v_fmac_f32_e32 v230, v212, v152
	v_fmac_f32_e32 v231, v213, v153
	ds_read2_b32 v[212:213], v229 offset0:32 offset1:34
	s_waitcnt lgkmcnt(11)
	v_fmac_f32_e32 v230, v214, v154
	v_fmac_f32_e32 v231, v215, v155
	ds_read2_b32 v[214:215], v229 offset0:36 offset1:38
	s_waitcnt lgkmcnt(11)
	v_fmac_f32_e32 v230, v216, v156
	v_fmac_f32_e32 v231, v217, v157
	ds_read2_b32 v[216:217], v229 offset0:40 offset1:42
	s_waitcnt lgkmcnt(11)
	v_fmac_f32_e32 v230, v224, v158
	v_fmac_f32_e32 v231, v225, v159
	v_add_f32_e32 v230, v230, v231
	s_nop 1
	v_add_f32_dpp v232, v230, v230 quad_perm:[1,0,3,2] row_mask:0xf bank_mask:0xf
	v_sub_f32_e32 v233, v159, v232
	v_cndmask_b32_e64 v159, v159, v233, s[4:5]
	ds_read2_b32 v[224:225], v229 offset0:44 offset1:46
	s_waitcnt lgkmcnt(11)
	v_mul_f32_e32 v230, v168, v136
	v_mul_f32_e32 v231, v169, v137
	v_add_u32_e32 v226, 0x2f00, v45
	ds_read2_b32 v[168:169], v226 offset0:0 offset1:2
	s_waitcnt lgkmcnt(11)
	v_fmac_f32_e32 v230, v170, v138
	v_fmac_f32_e32 v231, v171, v139
	ds_read2_b32 v[170:171], v226 offset0:4 offset1:6
	s_waitcnt lgkmcnt(11)
	v_fmac_f32_e32 v230, v172, v140
	v_fmac_f32_e32 v231, v173, v141
	ds_read2_b32 v[172:173], v226 offset0:8 offset1:10
	s_waitcnt lgkmcnt(11)
	v_fmac_f32_e32 v230, v174, v142
	v_fmac_f32_e32 v231, v175, v143
	ds_read2_b32 v[174:175], v226 offset0:12 offset1:14
	s_waitcnt lgkmcnt(11)
	v_fmac_f32_e32 v230, v176, v144
	v_fmac_f32_e32 v231, v177, v145
	ds_read2_b32 v[176:177], v226 offset0:16 offset1:18
	s_waitcnt lgkmcnt(11)
	v_fmac_f32_e32 v230, v178, v146
	v_fmac_f32_e32 v231, v179, v147
	ds_read2_b32 v[178:179], v226 offset0:20 offset1:22
	s_waitcnt lgkmcnt(11)
	v_fmac_f32_e32 v230, v180, v148
	v_fmac_f32_e32 v231, v181, v149
	ds_read2_b32 v[180:181], v226 offset0:24 offset1:26
	s_waitcnt lgkmcnt(11)
	v_fmac_f32_e32 v230, v210, v150
	v_fmac_f32_e32 v231, v211, v151
	ds_read2_b32 v[210:211], v226 offset0:28 offset1:30
	s_waitcnt lgkmcnt(11)
	v_fmac_f32_e32 v230, v212, v152
	v_fmac_f32_e32 v231, v213, v153
	ds_read2_b32 v[212:213], v226 offset0:32 offset1:34
	s_waitcnt lgkmcnt(11)
	v_fmac_f32_e32 v230, v214, v154
	v_fmac_f32_e32 v231, v215, v155
	ds_read2_b32 v[214:215], v226 offset0:36 offset1:38
	s_waitcnt lgkmcnt(11)
	v_fmac_f32_e32 v230, v216, v156
	v_fmac_f32_e32 v231, v217, v157
	ds_read2_b32 v[216:217], v226 offset0:40 offset1:42
	s_waitcnt lgkmcnt(11)
	v_fmac_f32_e32 v230, v224, v158
	v_fmac_f32_e32 v231, v225, v159
	v_add_f32_e32 v230, v230, v231
	s_nop 1
	v_add_f32_dpp v232, v230, v230 quad_perm:[1,0,3,2] row_mask:0xf bank_mask:0xf
	v_sub_f32_e32 v233, v159, v232
	v_cndmask_b32_e64 v159, v159, v233, s[8:9]
	ds_read2_b32 v[224:225], v226 offset0:44 offset1:46
	s_waitcnt lgkmcnt(11)
	v_mul_f32_e32 v230, v168, v136
	v_mul_f32_e32 v231, v169, v137
	v_add_u32_e32 v227, 0x3000, v45
	ds_read2_b32 v[168:169], v227 offset0:0 offset1:2
	s_waitcnt lgkmcnt(11)
	v_fmac_f32_e32 v230, v170, v138
	v_fmac_f32_e32 v231, v171, v139
	ds_read2_b32 v[170:171], v227 offset0:4 offset1:6
	s_waitcnt lgkmcnt(11)
	v_fmac_f32_e32 v230, v172, v140
	v_fmac_f32_e32 v231, v173, v141
	ds_read2_b32 v[172:173], v227 offset0:8 offset1:10
	s_waitcnt lgkmcnt(11)
	v_fmac_f32_e32 v230, v174, v142
	v_fmac_f32_e32 v231, v175, v143
	ds_read2_b32 v[174:175], v227 offset0:12 offset1:14
	s_waitcnt lgkmcnt(11)
	v_fmac_f32_e32 v230, v176, v144
	v_fmac_f32_e32 v231, v177, v145
	ds_read2_b32 v[176:177], v227 offset0:16 offset1:18
	s_waitcnt lgkmcnt(11)
	v_fmac_f32_e32 v230, v178, v146
	v_fmac_f32_e32 v231, v179, v147
	ds_read2_b32 v[178:179], v227 offset0:20 offset1:22
	s_waitcnt lgkmcnt(11)
	v_fmac_f32_e32 v230, v180, v148
	v_fmac_f32_e32 v231, v181, v149
	ds_read2_b32 v[180:181], v227 offset0:24 offset1:26
	s_waitcnt lgkmcnt(11)
	v_fmac_f32_e32 v230, v210, v150
	v_fmac_f32_e32 v231, v211, v151
	ds_read2_b32 v[210:211], v227 offset0:28 offset1:30
	s_waitcnt lgkmcnt(11)
	v_fmac_f32_e32 v230, v212, v152
	v_fmac_f32_e32 v231, v213, v153
	ds_read2_b32 v[212:213], v227 offset0:32 offset1:34
	s_waitcnt lgkmcnt(11)
	v_fmac_f32_e32 v230, v214, v154
	v_fmac_f32_e32 v231, v215, v155
	ds_read2_b32 v[214:215], v227 offset0:36 offset1:38
	s_waitcnt lgkmcnt(11)
	v_fmac_f32_e32 v230, v216, v156
	v_fmac_f32_e32 v231, v217, v157
	ds_read2_b32 v[216:217], v227 offset0:40 offset1:42
	s_waitcnt lgkmcnt(11)
	v_fmac_f32_e32 v230, v224, v158
	v_fmac_f32_e32 v231, v225, v159
	v_add_f32_e32 v230, v230, v231
	s_nop 1
	v_add_f32_dpp v232, v230, v230 quad_perm:[1,0,3,2] row_mask:0xf bank_mask:0xf
	v_sub_f32_e32 v233, v160, v232
	v_cndmask_b32_e64 v160, v160, v233, s[4:5]
	ds_read2_b32 v[224:225], v227 offset0:44 offset1:46
	s_waitcnt lgkmcnt(11)
	v_mul_f32_e32 v230, v168, v136
	v_mul_f32_e32 v231, v169, v137
	ds_read2_b32 v[168:169], v227 offset0:48 offset1:50
	s_waitcnt lgkmcnt(11)
	v_fmac_f32_e32 v230, v170, v138
	v_fmac_f32_e32 v231, v171, v139
	v_add_u32_e32 v228, 0x3100, v45
	ds_read2_b32 v[170:171], v228 offset0:0 offset1:2
	s_waitcnt lgkmcnt(11)
	v_fmac_f32_e32 v230, v172, v140
	v_fmac_f32_e32 v231, v173, v141
	ds_read2_b32 v[172:173], v228 offset0:4 offset1:6
	s_waitcnt lgkmcnt(11)
	v_fmac_f32_e32 v230, v174, v142
	v_fmac_f32_e32 v231, v175, v143
	ds_read2_b32 v[174:175], v228 offset0:8 offset1:10
	s_waitcnt lgkmcnt(11)
	v_fmac_f32_e32 v230, v176, v144
	v_fmac_f32_e32 v231, v177, v145
	ds_read2_b32 v[176:177], v228 offset0:12 offset1:14
	s_waitcnt lgkmcnt(11)
	v_fmac_f32_e32 v230, v178, v146
	v_fmac_f32_e32 v231, v179, v147
	ds_read2_b32 v[178:179], v228 offset0:16 offset1:18
	s_waitcnt lgkmcnt(11)
	v_fmac_f32_e32 v230, v180, v148
	v_fmac_f32_e32 v231, v181, v149
	ds_read2_b32 v[180:181], v228 offset0:20 offset1:22
	s_waitcnt lgkmcnt(11)
	v_fmac_f32_e32 v230, v210, v150
	v_fmac_f32_e32 v231, v211, v151
	ds_read2_b32 v[210:211], v228 offset0:24 offset1:26
	s_waitcnt lgkmcnt(11)
	v_fmac_f32_e32 v230, v212, v152
	v_fmac_f32_e32 v231, v213, v153
	ds_read2_b32 v[212:213], v228 offset0:28 offset1:30
	s_waitcnt lgkmcnt(11)
	v_fmac_f32_e32 v230, v214, v154
	v_fmac_f32_e32 v231, v215, v155
	ds_read2_b32 v[214:215], v228 offset0:32 offset1:34
	s_waitcnt lgkmcnt(11)
	v_fmac_f32_e32 v230, v216, v156
	v_fmac_f32_e32 v231, v217, v157
	ds_read2_b32 v[216:217], v228 offset0:36 offset1:38
	s_waitcnt lgkmcnt(11)
	v_fmac_f32_e32 v230, v224, v158
	v_fmac_f32_e32 v231, v225, v159
	ds_read2_b32 v[224:225], v228 offset0:40 offset1:42
	s_waitcnt lgkmcnt(11)
	v_fmac_f32_e32 v230, v168, v160
	v_fmac_f32_e32 v231, v169, v161
	v_add_f32_e32 v230, v230, v231
	s_nop 1
	v_add_f32_dpp v232, v230, v230 quad_perm:[1,0,3,2] row_mask:0xf bank_mask:0xf
	v_sub_f32_e32 v233, v160, v232
	v_cndmask_b32_e64 v160, v160, v233, s[8:9]
	ds_read2_b32 v[168:169], v228 offset0:44 offset1:46
	s_waitcnt lgkmcnt(11)
	v_mul_f32_e32 v230, v170, v136
	v_mul_f32_e32 v231, v171, v137
	ds_read2_b32 v[170:171], v228 offset0:48 offset1:50
	s_waitcnt lgkmcnt(11)
	v_fmac_f32_e32 v230, v172, v138
	v_fmac_f32_e32 v231, v173, v139
	v_add_u32_e32 v229, 0x3200, v45
	ds_read2_b32 v[172:173], v229 offset0:0 offset1:2
	s_waitcnt lgkmcnt(11)
	v_fmac_f32_e32 v230, v174, v140
	v_fmac_f32_e32 v231, v175, v141
	ds_read2_b32 v[174:175], v229 offset0:4 offset1:6
	s_waitcnt lgkmcnt(11)
	v_fmac_f32_e32 v230, v176, v142
	v_fmac_f32_e32 v231, v177, v143
	ds_read2_b32 v[176:177], v229 offset0:8 offset1:10
	s_waitcnt lgkmcnt(11)
	v_fmac_f32_e32 v230, v178, v144
	v_fmac_f32_e32 v231, v179, v145
	ds_read2_b32 v[178:179], v229 offset0:12 offset1:14
	s_waitcnt lgkmcnt(11)
	v_fmac_f32_e32 v230, v180, v146
	v_fmac_f32_e32 v231, v181, v147
	ds_read2_b32 v[180:181], v229 offset0:16 offset1:18
	s_waitcnt lgkmcnt(11)
	v_fmac_f32_e32 v230, v210, v148
	v_fmac_f32_e32 v231, v211, v149
	ds_read2_b32 v[210:211], v229 offset0:20 offset1:22
	s_waitcnt lgkmcnt(11)
	v_fmac_f32_e32 v230, v212, v150
	v_fmac_f32_e32 v231, v213, v151
	ds_read2_b32 v[212:213], v229 offset0:24 offset1:26
	s_waitcnt lgkmcnt(11)
	v_fmac_f32_e32 v230, v214, v152
	v_fmac_f32_e32 v231, v215, v153
	ds_read2_b32 v[214:215], v229 offset0:28 offset1:30
	s_waitcnt lgkmcnt(11)
	v_fmac_f32_e32 v230, v216, v154
	v_fmac_f32_e32 v231, v217, v155
	ds_read2_b32 v[216:217], v229 offset0:32 offset1:34
	s_waitcnt lgkmcnt(11)
	v_fmac_f32_e32 v230, v224, v156
	v_fmac_f32_e32 v231, v225, v157
	ds_read2_b32 v[224:225], v229 offset0:36 offset1:38
	s_waitcnt lgkmcnt(11)
	v_fmac_f32_e32 v230, v168, v158
	v_fmac_f32_e32 v231, v169, v159
	ds_read2_b32 v[168:169], v229 offset0:40 offset1:42
	s_waitcnt lgkmcnt(11)
	v_fmac_f32_e32 v230, v170, v160
	v_fmac_f32_e32 v231, v171, v161
	v_add_f32_e32 v230, v230, v231
	s_nop 1
	v_add_f32_dpp v232, v230, v230 quad_perm:[1,0,3,2] row_mask:0xf bank_mask:0xf
	v_sub_f32_e32 v233, v161, v232
	v_cndmask_b32_e64 v161, v161, v233, s[4:5]
	ds_read2_b32 v[170:171], v229 offset0:44 offset1:46
	s_waitcnt lgkmcnt(11)
	v_mul_f32_e32 v230, v172, v136
	v_mul_f32_e32 v231, v173, v137
	ds_read2_b32 v[172:173], v229 offset0:48 offset1:50
	s_waitcnt lgkmcnt(11)
	v_fmac_f32_e32 v230, v174, v138
	v_fmac_f32_e32 v231, v175, v139
	v_add_u32_e32 v226, 0x3300, v45
	ds_read2_b32 v[174:175], v226 offset0:0 offset1:2
	s_waitcnt lgkmcnt(11)
	v_fmac_f32_e32 v230, v176, v140
	v_fmac_f32_e32 v231, v177, v141
	ds_read2_b32 v[176:177], v226 offset0:4 offset1:6
	s_waitcnt lgkmcnt(11)
	v_fmac_f32_e32 v230, v178, v142
	v_fmac_f32_e32 v231, v179, v143
	ds_read2_b32 v[178:179], v226 offset0:8 offset1:10
	s_waitcnt lgkmcnt(11)
	v_fmac_f32_e32 v230, v180, v144
	v_fmac_f32_e32 v231, v181, v145
	ds_read2_b32 v[180:181], v226 offset0:12 offset1:14
	s_waitcnt lgkmcnt(11)
	v_fmac_f32_e32 v230, v210, v146
	v_fmac_f32_e32 v231, v211, v147
	ds_read2_b32 v[210:211], v226 offset0:16 offset1:18
	s_waitcnt lgkmcnt(11)
	v_fmac_f32_e32 v230, v212, v148
	v_fmac_f32_e32 v231, v213, v149
	ds_read2_b32 v[212:213], v226 offset0:20 offset1:22
	s_waitcnt lgkmcnt(11)
	v_fmac_f32_e32 v230, v214, v150
	v_fmac_f32_e32 v231, v215, v151
	ds_read2_b32 v[214:215], v226 offset0:24 offset1:26
	s_waitcnt lgkmcnt(11)
	v_fmac_f32_e32 v230, v216, v152
	v_fmac_f32_e32 v231, v217, v153
	ds_read2_b32 v[216:217], v226 offset0:28 offset1:30
	s_waitcnt lgkmcnt(11)
	v_fmac_f32_e32 v230, v224, v154
	v_fmac_f32_e32 v231, v225, v155
	ds_read2_b32 v[224:225], v226 offset0:32 offset1:34
	s_waitcnt lgkmcnt(11)
	v_fmac_f32_e32 v230, v168, v156
	v_fmac_f32_e32 v231, v169, v157
	ds_read2_b32 v[168:169], v226 offset0:36 offset1:38
	s_waitcnt lgkmcnt(11)
	v_fmac_f32_e32 v230, v170, v158
	v_fmac_f32_e32 v231, v171, v159
	ds_read2_b32 v[170:171], v226 offset0:40 offset1:42
	s_waitcnt lgkmcnt(11)
	v_fmac_f32_e32 v230, v172, v160
	v_fmac_f32_e32 v231, v173, v161
	v_add_f32_e32 v230, v230, v231
	s_nop 1
	v_add_f32_dpp v232, v230, v230 quad_perm:[1,0,3,2] row_mask:0xf bank_mask:0xf
	v_sub_f32_e32 v233, v161, v232
	v_cndmask_b32_e64 v161, v161, v233, s[8:9]
	ds_read2_b32 v[172:173], v226 offset0:44 offset1:46
	s_waitcnt lgkmcnt(11)
	v_mul_f32_e32 v230, v174, v136
	v_mul_f32_e32 v231, v175, v137
	ds_read2_b32 v[174:175], v226 offset0:48 offset1:50
	s_waitcnt lgkmcnt(11)
	v_fmac_f32_e32 v230, v176, v138
	v_fmac_f32_e32 v231, v177, v139
	v_add_u32_e32 v227, 0x3400, v45
	ds_read2_b32 v[176:177], v227 offset0:0 offset1:2
	s_waitcnt lgkmcnt(11)
	v_fmac_f32_e32 v230, v178, v140
	v_fmac_f32_e32 v231, v179, v141
	ds_read2_b32 v[178:179], v227 offset0:4 offset1:6
	s_waitcnt lgkmcnt(11)
	v_fmac_f32_e32 v230, v180, v142
	v_fmac_f32_e32 v231, v181, v143
	ds_read2_b32 v[180:181], v227 offset0:8 offset1:10
	s_waitcnt lgkmcnt(11)
	v_fmac_f32_e32 v230, v210, v144
	v_fmac_f32_e32 v231, v211, v145
	ds_read2_b32 v[210:211], v227 offset0:12 offset1:14
	s_waitcnt lgkmcnt(11)
	v_fmac_f32_e32 v230, v212, v146
	v_fmac_f32_e32 v231, v213, v147
	ds_read2_b32 v[212:213], v227 offset0:16 offset1:18
	s_waitcnt lgkmcnt(11)
	v_fmac_f32_e32 v230, v214, v148
	v_fmac_f32_e32 v231, v215, v149
	ds_read2_b32 v[214:215], v227 offset0:20 offset1:22
	s_waitcnt lgkmcnt(11)
	v_fmac_f32_e32 v230, v216, v150
	v_fmac_f32_e32 v231, v217, v151
	ds_read2_b32 v[216:217], v227 offset0:24 offset1:26
	s_waitcnt lgkmcnt(11)
	v_fmac_f32_e32 v230, v224, v152
	v_fmac_f32_e32 v231, v225, v153
	ds_read2_b32 v[224:225], v227 offset0:28 offset1:30
	s_waitcnt lgkmcnt(11)
	v_fmac_f32_e32 v230, v168, v154
	v_fmac_f32_e32 v231, v169, v155
	ds_read2_b32 v[168:169], v227 offset0:32 offset1:34
	s_waitcnt lgkmcnt(11)
	v_fmac_f32_e32 v230, v170, v156
	v_fmac_f32_e32 v231, v171, v157
	ds_read2_b32 v[170:171], v227 offset0:36 offset1:38
	s_waitcnt lgkmcnt(11)
	v_fmac_f32_e32 v230, v172, v158
	v_fmac_f32_e32 v231, v173, v159
	ds_read2_b32 v[172:173], v227 offset0:40 offset1:42
	s_waitcnt lgkmcnt(11)
	v_fmac_f32_e32 v230, v174, v160
	v_fmac_f32_e32 v231, v175, v161
	v_add_f32_e32 v230, v230, v231
	s_nop 1
	v_add_f32_dpp v232, v230, v230 quad_perm:[1,0,3,2] row_mask:0xf bank_mask:0xf
	v_sub_f32_e32 v233, v162, v232
	v_cndmask_b32_e64 v162, v162, v233, s[4:5]
	ds_read2_b32 v[174:175], v227 offset0:44 offset1:46
	s_waitcnt lgkmcnt(11)
	v_mul_f32_e32 v230, v176, v136
	v_mul_f32_e32 v231, v177, v137
	ds_read2_b32 v[176:177], v227 offset0:48 offset1:50
	s_waitcnt lgkmcnt(11)
	v_fmac_f32_e32 v230, v178, v138
	v_fmac_f32_e32 v231, v179, v139
	ds_read2_b32 v[178:179], v227 offset0:52 offset1:54
	s_waitcnt lgkmcnt(11)
	v_fmac_f32_e32 v230, v180, v140
	v_fmac_f32_e32 v231, v181, v141
	v_add_u32_e32 v228, 0x3500, v45
	ds_read2_b32 v[180:181], v228 offset0:0 offset1:2
	s_waitcnt lgkmcnt(11)
	v_fmac_f32_e32 v230, v210, v142
	v_fmac_f32_e32 v231, v211, v143
	ds_read2_b32 v[210:211], v228 offset0:4 offset1:6
	s_waitcnt lgkmcnt(11)
	v_fmac_f32_e32 v230, v212, v144
	v_fmac_f32_e32 v231, v213, v145
	ds_read2_b32 v[212:213], v228 offset0:8 offset1:10
	s_waitcnt lgkmcnt(11)
	v_fmac_f32_e32 v230, v214, v146
	v_fmac_f32_e32 v231, v215, v147
	ds_read2_b32 v[214:215], v228 offset0:12 offset1:14
	s_waitcnt lgkmcnt(11)
	v_fmac_f32_e32 v230, v216, v148
	v_fmac_f32_e32 v231, v217, v149
	ds_read2_b32 v[216:217], v228 offset0:16 offset1:18
	s_waitcnt lgkmcnt(11)
	v_fmac_f32_e32 v230, v224, v150
	v_fmac_f32_e32 v231, v225, v151
	ds_read2_b32 v[224:225], v228 offset0:20 offset1:22
	s_waitcnt lgkmcnt(11)
	v_fmac_f32_e32 v230, v168, v152
	v_fmac_f32_e32 v231, v169, v153
	ds_read2_b32 v[168:169], v228 offset0:24 offset1:26
	s_waitcnt lgkmcnt(11)
	v_fmac_f32_e32 v230, v170, v154
	v_fmac_f32_e32 v231, v171, v155
	ds_read2_b32 v[170:171], v228 offset0:28 offset1:30
	s_waitcnt lgkmcnt(11)
	v_fmac_f32_e32 v230, v172, v156
	v_fmac_f32_e32 v231, v173, v157
	ds_read2_b32 v[172:173], v228 offset0:32 offset1:34
	s_waitcnt lgkmcnt(11)
	v_fmac_f32_e32 v230, v174, v158
	v_fmac_f32_e32 v231, v175, v159
	ds_read2_b32 v[174:175], v228 offset0:36 offset1:38
	s_waitcnt lgkmcnt(11)
	v_fmac_f32_e32 v230, v176, v160
	v_fmac_f32_e32 v231, v177, v161
	ds_read2_b32 v[176:177], v228 offset0:40 offset1:42
	s_waitcnt lgkmcnt(11)
	v_fmac_f32_e32 v230, v178, v162
	v_fmac_f32_e32 v231, v179, v163
	v_add_f32_e32 v230, v230, v231
	s_nop 1
	v_add_f32_dpp v232, v230, v230 quad_perm:[1,0,3,2] row_mask:0xf bank_mask:0xf
	v_sub_f32_e32 v233, v162, v232
	v_cndmask_b32_e64 v162, v162, v233, s[8:9]
	ds_read2_b32 v[178:179], v228 offset0:44 offset1:46
	s_waitcnt lgkmcnt(11)
	v_mul_f32_e32 v230, v180, v136
	v_mul_f32_e32 v231, v181, v137
	ds_read2_b32 v[180:181], v228 offset0:48 offset1:50
	s_waitcnt lgkmcnt(11)
	v_fmac_f32_e32 v230, v210, v138
	v_fmac_f32_e32 v231, v211, v139
	ds_read2_b32 v[210:211], v228 offset0:52 offset1:54
	s_waitcnt lgkmcnt(11)
	v_fmac_f32_e32 v230, v212, v140
	v_fmac_f32_e32 v231, v213, v141
	v_add_u32_e32 v229, 0x3600, v45
	ds_read2_b32 v[212:213], v229 offset0:0 offset1:2
	s_waitcnt lgkmcnt(11)
	v_fmac_f32_e32 v230, v214, v142
	v_fmac_f32_e32 v231, v215, v143
	ds_read2_b32 v[214:215], v229 offset0:4 offset1:6
	s_waitcnt lgkmcnt(11)
	v_fmac_f32_e32 v230, v216, v144
	v_fmac_f32_e32 v231, v217, v145
	ds_read2_b32 v[216:217], v229 offset0:8 offset1:10
	s_waitcnt lgkmcnt(11)
	v_fmac_f32_e32 v230, v224, v146
	v_fmac_f32_e32 v231, v225, v147
	ds_read2_b32 v[224:225], v229 offset0:12 offset1:14
	s_waitcnt lgkmcnt(11)
	v_fmac_f32_e32 v230, v168, v148
	v_fmac_f32_e32 v231, v169, v149
	ds_read2_b32 v[168:169], v229 offset0:16 offset1:18
	s_waitcnt lgkmcnt(11)
	v_fmac_f32_e32 v230, v170, v150
	v_fmac_f32_e32 v231, v171, v151
	ds_read2_b32 v[170:171], v229 offset0:20 offset1:22
	s_waitcnt lgkmcnt(11)
	v_fmac_f32_e32 v230, v172, v152
	v_fmac_f32_e32 v231, v173, v153
	ds_read2_b32 v[172:173], v229 offset0:24 offset1:26
	s_waitcnt lgkmcnt(11)
	v_fmac_f32_e32 v230, v174, v154
	v_fmac_f32_e32 v231, v175, v155
	ds_read2_b32 v[174:175], v229 offset0:28 offset1:30
	s_waitcnt lgkmcnt(11)
	v_fmac_f32_e32 v230, v176, v156
	v_fmac_f32_e32 v231, v177, v157
	ds_read2_b32 v[176:177], v229 offset0:32 offset1:34
	s_waitcnt lgkmcnt(11)
	v_fmac_f32_e32 v230, v178, v158
	v_fmac_f32_e32 v231, v179, v159
	ds_read2_b32 v[178:179], v229 offset0:36 offset1:38
	s_waitcnt lgkmcnt(11)
	v_fmac_f32_e32 v230, v180, v160
	v_fmac_f32_e32 v231, v181, v161
	ds_read2_b32 v[180:181], v229 offset0:40 offset1:42
	s_waitcnt lgkmcnt(11)
	v_fmac_f32_e32 v230, v210, v162
	v_fmac_f32_e32 v231, v211, v163
	v_add_f32_e32 v230, v230, v231
	s_nop 1
	v_add_f32_dpp v232, v230, v230 quad_perm:[1,0,3,2] row_mask:0xf bank_mask:0xf
	v_sub_f32_e32 v233, v163, v232
	v_cndmask_b32_e64 v163, v163, v233, s[4:5]
	ds_read2_b32 v[210:211], v229 offset0:44 offset1:46
	s_waitcnt lgkmcnt(11)
	v_mul_f32_e32 v230, v212, v136
	v_mul_f32_e32 v231, v213, v137
	ds_read2_b32 v[212:213], v229 offset0:48 offset1:50
	s_waitcnt lgkmcnt(11)
	v_fmac_f32_e32 v230, v214, v138
	v_fmac_f32_e32 v231, v215, v139
	ds_read2_b32 v[214:215], v229 offset0:52 offset1:54
	s_waitcnt lgkmcnt(11)
	v_fmac_f32_e32 v230, v216, v140
	v_fmac_f32_e32 v231, v217, v141
	v_add_u32_e32 v226, 0x3700, v45
	ds_read2_b32 v[216:217], v226 offset0:0 offset1:2
	s_waitcnt lgkmcnt(11)
	v_fmac_f32_e32 v230, v224, v142
	v_fmac_f32_e32 v231, v225, v143
	ds_read2_b32 v[224:225], v226 offset0:4 offset1:6
	s_waitcnt lgkmcnt(11)
	v_fmac_f32_e32 v230, v168, v144
	v_fmac_f32_e32 v231, v169, v145
	ds_read2_b32 v[168:169], v226 offset0:8 offset1:10
	s_waitcnt lgkmcnt(11)
	v_fmac_f32_e32 v230, v170, v146
	v_fmac_f32_e32 v231, v171, v147
	ds_read2_b32 v[170:171], v226 offset0:12 offset1:14
	s_waitcnt lgkmcnt(11)
	v_fmac_f32_e32 v230, v172, v148
	v_fmac_f32_e32 v231, v173, v149
	ds_read2_b32 v[172:173], v226 offset0:16 offset1:18
	s_waitcnt lgkmcnt(11)
	v_fmac_f32_e32 v230, v174, v150
	v_fmac_f32_e32 v231, v175, v151
	ds_read2_b32 v[174:175], v226 offset0:20 offset1:22
	s_waitcnt lgkmcnt(11)
	v_fmac_f32_e32 v230, v176, v152
	v_fmac_f32_e32 v231, v177, v153
	ds_read2_b32 v[176:177], v226 offset0:24 offset1:26
	s_waitcnt lgkmcnt(11)
	v_fmac_f32_e32 v230, v178, v154
	v_fmac_f32_e32 v231, v179, v155
	ds_read2_b32 v[178:179], v226 offset0:28 offset1:30
	s_waitcnt lgkmcnt(11)
	v_fmac_f32_e32 v230, v180, v156
	v_fmac_f32_e32 v231, v181, v157
	ds_read2_b32 v[180:181], v226 offset0:32 offset1:34
	s_waitcnt lgkmcnt(11)
	v_fmac_f32_e32 v230, v210, v158
	v_fmac_f32_e32 v231, v211, v159
	ds_read2_b32 v[210:211], v226 offset0:36 offset1:38
	s_waitcnt lgkmcnt(11)
	v_fmac_f32_e32 v230, v212, v160
	v_fmac_f32_e32 v231, v213, v161
	ds_read2_b32 v[212:213], v226 offset0:40 offset1:42
	s_waitcnt lgkmcnt(11)
	v_fmac_f32_e32 v230, v214, v162
	v_fmac_f32_e32 v231, v215, v163
	v_add_f32_e32 v230, v230, v231
	s_nop 1
	v_add_f32_dpp v232, v230, v230 quad_perm:[1,0,3,2] row_mask:0xf bank_mask:0xf
	v_sub_f32_e32 v233, v163, v232
	v_cndmask_b32_e64 v163, v163, v233, s[8:9]
	ds_read2_b32 v[214:215], v226 offset0:44 offset1:46
	s_waitcnt lgkmcnt(11)
	v_mul_f32_e32 v230, v216, v136
	v_mul_f32_e32 v231, v217, v137
	ds_read2_b32 v[216:217], v226 offset0:48 offset1:50
	s_waitcnt lgkmcnt(11)
	v_fmac_f32_e32 v230, v224, v138
	v_fmac_f32_e32 v231, v225, v139
	ds_read2_b32 v[224:225], v226 offset0:52 offset1:54
	s_waitcnt lgkmcnt(11)
	v_fmac_f32_e32 v230, v168, v140
	v_fmac_f32_e32 v231, v169, v141
	v_add_u32_e32 v227, 0x3800, v45
	ds_read2_b32 v[168:169], v227 offset0:0 offset1:2
	s_waitcnt lgkmcnt(11)
	v_fmac_f32_e32 v230, v170, v142
	v_fmac_f32_e32 v231, v171, v143
	ds_read2_b32 v[170:171], v227 offset0:4 offset1:6
	s_waitcnt lgkmcnt(11)
	v_fmac_f32_e32 v230, v172, v144
	v_fmac_f32_e32 v231, v173, v145
	ds_read2_b32 v[172:173], v227 offset0:8 offset1:10
	s_waitcnt lgkmcnt(11)
	v_fmac_f32_e32 v230, v174, v146
	v_fmac_f32_e32 v231, v175, v147
	ds_read2_b32 v[174:175], v227 offset0:12 offset1:14
	s_waitcnt lgkmcnt(11)
	v_fmac_f32_e32 v230, v176, v148
	v_fmac_f32_e32 v231, v177, v149
	ds_read2_b32 v[176:177], v227 offset0:16 offset1:18
	s_waitcnt lgkmcnt(11)
	v_fmac_f32_e32 v230, v178, v150
	v_fmac_f32_e32 v231, v179, v151
	ds_read2_b32 v[178:179], v227 offset0:20 offset1:22
	s_waitcnt lgkmcnt(11)
	v_fmac_f32_e32 v230, v180, v152
	v_fmac_f32_e32 v231, v181, v153
	ds_read2_b32 v[180:181], v227 offset0:24 offset1:26
	s_waitcnt lgkmcnt(11)
	v_fmac_f32_e32 v230, v210, v154
	v_fmac_f32_e32 v231, v211, v155
	ds_read2_b32 v[210:211], v227 offset0:28 offset1:30
	s_waitcnt lgkmcnt(11)
	v_fmac_f32_e32 v230, v212, v156
	v_fmac_f32_e32 v231, v213, v157
	ds_read2_b32 v[212:213], v227 offset0:32 offset1:34
	s_waitcnt lgkmcnt(11)
	v_fmac_f32_e32 v230, v214, v158
	v_fmac_f32_e32 v231, v215, v159
	ds_read2_b32 v[214:215], v227 offset0:36 offset1:38
	s_waitcnt lgkmcnt(11)
	v_fmac_f32_e32 v230, v216, v160
	v_fmac_f32_e32 v231, v217, v161
	ds_read2_b32 v[216:217], v227 offset0:40 offset1:42
	s_waitcnt lgkmcnt(11)
	v_fmac_f32_e32 v230, v224, v162
	v_fmac_f32_e32 v231, v225, v163
	v_add_f32_e32 v230, v230, v231
	s_nop 1
	v_add_f32_dpp v232, v230, v230 quad_perm:[1,0,3,2] row_mask:0xf bank_mask:0xf
	v_sub_f32_e32 v233, v164, v232
	v_cndmask_b32_e64 v164, v164, v233, s[4:5]
	ds_read2_b32 v[224:225], v227 offset0:44 offset1:46
	s_waitcnt lgkmcnt(11)
	v_mul_f32_e32 v230, v168, v136
	v_mul_f32_e32 v231, v169, v137
	ds_read2_b32 v[168:169], v227 offset0:48 offset1:50
	s_waitcnt lgkmcnt(11)
	v_fmac_f32_e32 v230, v170, v138
	v_fmac_f32_e32 v231, v171, v139
	ds_read2_b32 v[170:171], v227 offset0:52 offset1:54
	s_waitcnt lgkmcnt(11)
	v_fmac_f32_e32 v230, v172, v140
	v_fmac_f32_e32 v231, v173, v141
	ds_read2_b32 v[172:173], v227 offset0:56 offset1:58
	s_waitcnt lgkmcnt(11)
	v_fmac_f32_e32 v230, v174, v142
	v_fmac_f32_e32 v231, v175, v143
	v_add_u32_e32 v228, 0x3900, v45
	ds_read2_b32 v[174:175], v228 offset0:0 offset1:2
	s_waitcnt lgkmcnt(11)
	v_fmac_f32_e32 v230, v176, v144
	v_fmac_f32_e32 v231, v177, v145
	ds_read2_b32 v[176:177], v228 offset0:4 offset1:6
	s_waitcnt lgkmcnt(11)
	v_fmac_f32_e32 v230, v178, v146
	v_fmac_f32_e32 v231, v179, v147
	ds_read2_b32 v[178:179], v228 offset0:8 offset1:10
	s_waitcnt lgkmcnt(11)
	v_fmac_f32_e32 v230, v180, v148
	v_fmac_f32_e32 v231, v181, v149
	ds_read2_b32 v[180:181], v228 offset0:12 offset1:14
	s_waitcnt lgkmcnt(11)
	v_fmac_f32_e32 v230, v210, v150
	v_fmac_f32_e32 v231, v211, v151
	ds_read2_b32 v[210:211], v228 offset0:16 offset1:18
	s_waitcnt lgkmcnt(11)
	v_fmac_f32_e32 v230, v212, v152
	v_fmac_f32_e32 v231, v213, v153
	ds_read2_b32 v[212:213], v228 offset0:20 offset1:22
	s_waitcnt lgkmcnt(11)
	v_fmac_f32_e32 v230, v214, v154
	v_fmac_f32_e32 v231, v215, v155
	ds_read2_b32 v[214:215], v228 offset0:24 offset1:26
	s_waitcnt lgkmcnt(11)
	v_fmac_f32_e32 v230, v216, v156
	v_fmac_f32_e32 v231, v217, v157
	ds_read2_b32 v[216:217], v228 offset0:28 offset1:30
	s_waitcnt lgkmcnt(11)
	v_fmac_f32_e32 v230, v224, v158
	v_fmac_f32_e32 v231, v225, v159
	ds_read2_b32 v[224:225], v228 offset0:32 offset1:34
	s_waitcnt lgkmcnt(11)
	v_fmac_f32_e32 v230, v168, v160
	v_fmac_f32_e32 v231, v169, v161
	ds_read2_b32 v[168:169], v228 offset0:36 offset1:38
	s_waitcnt lgkmcnt(11)
	v_fmac_f32_e32 v230, v170, v162
	v_fmac_f32_e32 v231, v171, v163
	ds_read2_b32 v[170:171], v228 offset0:40 offset1:42
	s_waitcnt lgkmcnt(11)
	v_fmac_f32_e32 v230, v172, v164
	v_fmac_f32_e32 v231, v173, v165
	v_add_f32_e32 v230, v230, v231
	s_nop 1
	v_add_f32_dpp v232, v230, v230 quad_perm:[1,0,3,2] row_mask:0xf bank_mask:0xf
	v_sub_f32_e32 v233, v164, v232
	v_cndmask_b32_e64 v164, v164, v233, s[8:9]
	ds_read2_b32 v[172:173], v228 offset0:44 offset1:46
	s_waitcnt lgkmcnt(11)
	v_mul_f32_e32 v230, v174, v136
	v_mul_f32_e32 v231, v175, v137
	ds_read2_b32 v[174:175], v228 offset0:48 offset1:50
	s_waitcnt lgkmcnt(11)
	v_fmac_f32_e32 v230, v176, v138
	v_fmac_f32_e32 v231, v177, v139
	ds_read2_b32 v[176:177], v228 offset0:52 offset1:54
	s_waitcnt lgkmcnt(11)
	v_fmac_f32_e32 v230, v178, v140
	v_fmac_f32_e32 v231, v179, v141
	ds_read2_b32 v[178:179], v228 offset0:56 offset1:58
	s_waitcnt lgkmcnt(11)
	v_fmac_f32_e32 v230, v180, v142
	v_fmac_f32_e32 v231, v181, v143
	v_add_u32_e32 v229, 0x3a00, v45
	ds_read2_b32 v[180:181], v229 offset0:0 offset1:2
	s_waitcnt lgkmcnt(11)
	v_fmac_f32_e32 v230, v210, v144
	v_fmac_f32_e32 v231, v211, v145
	ds_read2_b32 v[210:211], v229 offset0:4 offset1:6
	s_waitcnt lgkmcnt(11)
	v_fmac_f32_e32 v230, v212, v146
	v_fmac_f32_e32 v231, v213, v147
	ds_read2_b32 v[212:213], v229 offset0:8 offset1:10
	s_waitcnt lgkmcnt(11)
	v_fmac_f32_e32 v230, v214, v148
	v_fmac_f32_e32 v231, v215, v149
	ds_read2_b32 v[214:215], v229 offset0:12 offset1:14
	s_waitcnt lgkmcnt(11)
	v_fmac_f32_e32 v230, v216, v150
	v_fmac_f32_e32 v231, v217, v151
	ds_read2_b32 v[216:217], v229 offset0:16 offset1:18
	s_waitcnt lgkmcnt(11)
	v_fmac_f32_e32 v230, v224, v152
	v_fmac_f32_e32 v231, v225, v153
	ds_read2_b32 v[224:225], v229 offset0:20 offset1:22
	s_waitcnt lgkmcnt(11)
	v_fmac_f32_e32 v230, v168, v154
	v_fmac_f32_e32 v231, v169, v155
	ds_read2_b32 v[168:169], v229 offset0:24 offset1:26
	s_waitcnt lgkmcnt(11)
	v_fmac_f32_e32 v230, v170, v156
	v_fmac_f32_e32 v231, v171, v157
	ds_read2_b32 v[170:171], v229 offset0:28 offset1:30
	s_waitcnt lgkmcnt(11)
	v_fmac_f32_e32 v230, v172, v158
	v_fmac_f32_e32 v231, v173, v159
	ds_read2_b32 v[172:173], v229 offset0:32 offset1:34
	s_waitcnt lgkmcnt(11)
	v_fmac_f32_e32 v230, v174, v160
	v_fmac_f32_e32 v231, v175, v161
	ds_read2_b32 v[174:175], v229 offset0:36 offset1:38
	s_waitcnt lgkmcnt(11)
	v_fmac_f32_e32 v230, v176, v162
	v_fmac_f32_e32 v231, v177, v163
	ds_read2_b32 v[176:177], v229 offset0:40 offset1:42
	s_waitcnt lgkmcnt(11)
	v_fmac_f32_e32 v230, v178, v164
	v_fmac_f32_e32 v231, v179, v165
	v_add_f32_e32 v230, v230, v231
	s_nop 1
	v_add_f32_dpp v232, v230, v230 quad_perm:[1,0,3,2] row_mask:0xf bank_mask:0xf
	v_sub_f32_e32 v233, v165, v232
	v_cndmask_b32_e64 v165, v165, v233, s[4:5]
	ds_read2_b32 v[178:179], v229 offset0:44 offset1:46
	s_waitcnt lgkmcnt(11)
	v_mul_f32_e32 v230, v180, v136
	v_mul_f32_e32 v231, v181, v137
	ds_read2_b32 v[180:181], v229 offset0:48 offset1:50
	s_waitcnt lgkmcnt(11)
	v_fmac_f32_e32 v230, v210, v138
	v_fmac_f32_e32 v231, v211, v139
	ds_read2_b32 v[210:211], v229 offset0:52 offset1:54
	s_waitcnt lgkmcnt(11)
	v_fmac_f32_e32 v230, v212, v140
	v_fmac_f32_e32 v231, v213, v141
	ds_read2_b32 v[212:213], v229 offset0:56 offset1:58
	s_waitcnt lgkmcnt(11)
	v_fmac_f32_e32 v230, v214, v142
	v_fmac_f32_e32 v231, v215, v143
	v_add_u32_e32 v226, 0x3b00, v45
	ds_read2_b32 v[214:215], v226 offset0:0 offset1:2
	s_waitcnt lgkmcnt(11)
	v_fmac_f32_e32 v230, v216, v144
	v_fmac_f32_e32 v231, v217, v145
	ds_read2_b32 v[216:217], v226 offset0:4 offset1:6
	s_waitcnt lgkmcnt(11)
	v_fmac_f32_e32 v230, v224, v146
	v_fmac_f32_e32 v231, v225, v147
	ds_read2_b32 v[224:225], v226 offset0:8 offset1:10
	s_waitcnt lgkmcnt(11)
	v_fmac_f32_e32 v230, v168, v148
	v_fmac_f32_e32 v231, v169, v149
	ds_read2_b32 v[168:169], v226 offset0:12 offset1:14
	s_waitcnt lgkmcnt(11)
	v_fmac_f32_e32 v230, v170, v150
	v_fmac_f32_e32 v231, v171, v151
	ds_read2_b32 v[170:171], v226 offset0:16 offset1:18
	s_waitcnt lgkmcnt(11)
	v_fmac_f32_e32 v230, v172, v152
	v_fmac_f32_e32 v231, v173, v153
	ds_read2_b32 v[172:173], v226 offset0:20 offset1:22
	s_waitcnt lgkmcnt(11)
	v_fmac_f32_e32 v230, v174, v154
	v_fmac_f32_e32 v231, v175, v155
	ds_read2_b32 v[174:175], v226 offset0:24 offset1:26
	s_waitcnt lgkmcnt(11)
	v_fmac_f32_e32 v230, v176, v156
	v_fmac_f32_e32 v231, v177, v157
	ds_read2_b32 v[176:177], v226 offset0:28 offset1:30
	s_waitcnt lgkmcnt(11)
	v_fmac_f32_e32 v230, v178, v158
	v_fmac_f32_e32 v231, v179, v159
	ds_read2_b32 v[178:179], v226 offset0:32 offset1:34
	s_waitcnt lgkmcnt(11)
	v_fmac_f32_e32 v230, v180, v160
	v_fmac_f32_e32 v231, v181, v161
	ds_read2_b32 v[180:181], v226 offset0:36 offset1:38
	s_waitcnt lgkmcnt(11)
	v_fmac_f32_e32 v230, v210, v162
	v_fmac_f32_e32 v231, v211, v163
	ds_read2_b32 v[210:211], v226 offset0:40 offset1:42
	s_waitcnt lgkmcnt(11)
	v_fmac_f32_e32 v230, v212, v164
	v_fmac_f32_e32 v231, v213, v165
	v_add_f32_e32 v230, v230, v231
	s_nop 1
	v_add_f32_dpp v232, v230, v230 quad_perm:[1,0,3,2] row_mask:0xf bank_mask:0xf
	v_sub_f32_e32 v233, v165, v232
	v_cndmask_b32_e64 v165, v165, v233, s[8:9]
	ds_read2_b32 v[212:213], v226 offset0:44 offset1:46
	s_waitcnt lgkmcnt(11)
	v_mul_f32_e32 v230, v214, v136
	v_mul_f32_e32 v231, v215, v137
	ds_read2_b32 v[214:215], v226 offset0:48 offset1:50
	s_waitcnt lgkmcnt(11)
	v_fmac_f32_e32 v230, v216, v138
	v_fmac_f32_e32 v231, v217, v139
	ds_read2_b32 v[216:217], v226 offset0:52 offset1:54
	s_waitcnt lgkmcnt(11)
	v_fmac_f32_e32 v230, v224, v140
	v_fmac_f32_e32 v231, v225, v141
	ds_read2_b32 v[224:225], v226 offset0:56 offset1:58
	s_waitcnt lgkmcnt(11)
	v_fmac_f32_e32 v230, v168, v142
	v_fmac_f32_e32 v231, v169, v143
	v_add_u32_e32 v227, 0x3c00, v45
	ds_read2_b32 v[168:169], v227 offset0:0 offset1:2
	s_waitcnt lgkmcnt(11)
	v_fmac_f32_e32 v230, v170, v144
	v_fmac_f32_e32 v231, v171, v145
	ds_read2_b32 v[170:171], v227 offset0:4 offset1:6
	s_waitcnt lgkmcnt(11)
	v_fmac_f32_e32 v230, v172, v146
	v_fmac_f32_e32 v231, v173, v147
	ds_read2_b32 v[172:173], v227 offset0:8 offset1:10
	s_waitcnt lgkmcnt(11)
	v_fmac_f32_e32 v230, v174, v148
	v_fmac_f32_e32 v231, v175, v149
	ds_read2_b32 v[174:175], v227 offset0:12 offset1:14
	s_waitcnt lgkmcnt(11)
	v_fmac_f32_e32 v230, v176, v150
	v_fmac_f32_e32 v231, v177, v151
	ds_read2_b32 v[176:177], v227 offset0:16 offset1:18
	s_waitcnt lgkmcnt(11)
	v_fmac_f32_e32 v230, v178, v152
	v_fmac_f32_e32 v231, v179, v153
	ds_read2_b32 v[178:179], v227 offset0:20 offset1:22
	s_waitcnt lgkmcnt(11)
	v_fmac_f32_e32 v230, v180, v154
	v_fmac_f32_e32 v231, v181, v155
	ds_read2_b32 v[180:181], v227 offset0:24 offset1:26
	s_waitcnt lgkmcnt(11)
	v_fmac_f32_e32 v230, v210, v156
	v_fmac_f32_e32 v231, v211, v157
	ds_read2_b32 v[210:211], v227 offset0:28 offset1:30
	s_waitcnt lgkmcnt(11)
	v_fmac_f32_e32 v230, v212, v158
	v_fmac_f32_e32 v231, v213, v159
	ds_read2_b32 v[212:213], v227 offset0:32 offset1:34
	s_waitcnt lgkmcnt(11)
	v_fmac_f32_e32 v230, v214, v160
	v_fmac_f32_e32 v231, v215, v161
	ds_read2_b32 v[214:215], v227 offset0:36 offset1:38
	s_waitcnt lgkmcnt(11)
	v_fmac_f32_e32 v230, v216, v162
	v_fmac_f32_e32 v231, v217, v163
	ds_read2_b32 v[216:217], v227 offset0:40 offset1:42
	s_waitcnt lgkmcnt(11)
	v_fmac_f32_e32 v230, v224, v164
	v_fmac_f32_e32 v231, v225, v165
	v_add_f32_e32 v230, v230, v231
	s_nop 1
	v_add_f32_dpp v232, v230, v230 quad_perm:[1,0,3,2] row_mask:0xf bank_mask:0xf
	v_sub_f32_e32 v233, v166, v232
	v_cndmask_b32_e64 v166, v166, v233, s[4:5]
	ds_read2_b32 v[224:225], v227 offset0:44 offset1:46
	s_waitcnt lgkmcnt(11)
	v_mul_f32_e32 v230, v168, v136
	v_mul_f32_e32 v231, v169, v137
	ds_read2_b32 v[168:169], v227 offset0:48 offset1:50
	s_waitcnt lgkmcnt(11)
	v_fmac_f32_e32 v230, v170, v138
	v_fmac_f32_e32 v231, v171, v139
	ds_read2_b32 v[170:171], v227 offset0:52 offset1:54
	s_waitcnt lgkmcnt(11)
	v_fmac_f32_e32 v230, v172, v140
	v_fmac_f32_e32 v231, v173, v141
	ds_read2_b32 v[172:173], v227 offset0:56 offset1:58
	s_waitcnt lgkmcnt(11)
	v_fmac_f32_e32 v230, v174, v142
	v_fmac_f32_e32 v231, v175, v143
	ds_read2_b32 v[174:175], v227 offset0:60 offset1:62
	s_waitcnt lgkmcnt(11)
	v_fmac_f32_e32 v230, v176, v144
	v_fmac_f32_e32 v231, v177, v145
	v_add_u32_e32 v228, 0x3d00, v45
	ds_read2_b32 v[176:177], v228 offset0:0 offset1:2
	s_waitcnt lgkmcnt(11)
	v_fmac_f32_e32 v230, v178, v146
	v_fmac_f32_e32 v231, v179, v147
	ds_read2_b32 v[178:179], v228 offset0:4 offset1:6
	s_waitcnt lgkmcnt(11)
	v_fmac_f32_e32 v230, v180, v148
	v_fmac_f32_e32 v231, v181, v149
	ds_read2_b32 v[180:181], v228 offset0:8 offset1:10
	s_waitcnt lgkmcnt(11)
	v_fmac_f32_e32 v230, v210, v150
	v_fmac_f32_e32 v231, v211, v151
	ds_read2_b32 v[210:211], v228 offset0:12 offset1:14
	s_waitcnt lgkmcnt(11)
	v_fmac_f32_e32 v230, v212, v152
	v_fmac_f32_e32 v231, v213, v153
	ds_read2_b32 v[212:213], v228 offset0:16 offset1:18
	s_waitcnt lgkmcnt(11)
	v_fmac_f32_e32 v230, v214, v154
	v_fmac_f32_e32 v231, v215, v155
	ds_read2_b32 v[214:215], v228 offset0:20 offset1:22
	s_waitcnt lgkmcnt(11)
	v_fmac_f32_e32 v230, v216, v156
	v_fmac_f32_e32 v231, v217, v157
	ds_read2_b32 v[216:217], v228 offset0:24 offset1:26
	s_waitcnt lgkmcnt(11)
	v_fmac_f32_e32 v230, v224, v158
	v_fmac_f32_e32 v231, v225, v159
	ds_read2_b32 v[224:225], v228 offset0:28 offset1:30
	s_waitcnt lgkmcnt(11)
	v_fmac_f32_e32 v230, v168, v160
	v_fmac_f32_e32 v231, v169, v161
	ds_read2_b32 v[168:169], v228 offset0:32 offset1:34
	s_waitcnt lgkmcnt(11)
	v_fmac_f32_e32 v230, v170, v162
	v_fmac_f32_e32 v231, v171, v163
	ds_read2_b32 v[170:171], v228 offset0:36 offset1:38
	s_waitcnt lgkmcnt(11)
	v_fmac_f32_e32 v230, v172, v164
	v_fmac_f32_e32 v231, v173, v165
	ds_read2_b32 v[172:173], v228 offset0:40 offset1:42
	s_waitcnt lgkmcnt(11)
	v_fmac_f32_e32 v230, v174, v166
	v_fmac_f32_e32 v231, v175, v167
	v_add_f32_e32 v230, v230, v231
	s_nop 1
	v_add_f32_dpp v232, v230, v230 quad_perm:[1,0,3,2] row_mask:0xf bank_mask:0xf
	v_sub_f32_e32 v233, v166, v232
	v_cndmask_b32_e64 v166, v166, v233, s[8:9]
	ds_read2_b32 v[174:175], v228 offset0:44 offset1:46
	s_waitcnt lgkmcnt(11)
	v_mul_f32_e32 v230, v176, v136
	v_mul_f32_e32 v231, v177, v137
	ds_read2_b32 v[176:177], v228 offset0:48 offset1:50
	s_waitcnt lgkmcnt(11)
	v_fmac_f32_e32 v230, v178, v138
	v_fmac_f32_e32 v231, v179, v139
	ds_read2_b32 v[178:179], v228 offset0:52 offset1:54
	s_waitcnt lgkmcnt(11)
	v_fmac_f32_e32 v230, v180, v140
	v_fmac_f32_e32 v231, v181, v141
	ds_read2_b32 v[180:181], v228 offset0:56 offset1:58
	s_waitcnt lgkmcnt(11)
	v_fmac_f32_e32 v230, v210, v142
	v_fmac_f32_e32 v231, v211, v143
	ds_read2_b32 v[210:211], v228 offset0:60 offset1:62
	s_waitcnt lgkmcnt(11)
	v_fmac_f32_e32 v230, v212, v144
	v_fmac_f32_e32 v231, v213, v145
	v_add_u32_e32 v229, 0x3e00, v45
	ds_read2_b32 v[212:213], v229 offset0:0 offset1:2
	s_waitcnt lgkmcnt(11)
	v_fmac_f32_e32 v230, v214, v146
	v_fmac_f32_e32 v231, v215, v147
	ds_read2_b32 v[214:215], v229 offset0:4 offset1:6
	s_waitcnt lgkmcnt(11)
	v_fmac_f32_e32 v230, v216, v148
	v_fmac_f32_e32 v231, v217, v149
	ds_read2_b32 v[216:217], v229 offset0:8 offset1:10
	s_waitcnt lgkmcnt(11)
	v_fmac_f32_e32 v230, v224, v150
	v_fmac_f32_e32 v231, v225, v151
	ds_read2_b32 v[224:225], v229 offset0:12 offset1:14
	s_waitcnt lgkmcnt(11)
	v_fmac_f32_e32 v230, v168, v152
	v_fmac_f32_e32 v231, v169, v153
	ds_read2_b32 v[168:169], v229 offset0:16 offset1:18
	s_waitcnt lgkmcnt(11)
	v_fmac_f32_e32 v230, v170, v154
	v_fmac_f32_e32 v231, v171, v155
	ds_read2_b32 v[170:171], v229 offset0:20 offset1:22
	s_waitcnt lgkmcnt(11)
	v_fmac_f32_e32 v230, v172, v156
	v_fmac_f32_e32 v231, v173, v157
	ds_read2_b32 v[172:173], v229 offset0:24 offset1:26
	s_waitcnt lgkmcnt(11)
	v_fmac_f32_e32 v230, v174, v158
	v_fmac_f32_e32 v231, v175, v159
	ds_read2_b32 v[174:175], v229 offset0:28 offset1:30
	s_waitcnt lgkmcnt(11)
	v_fmac_f32_e32 v230, v176, v160
	v_fmac_f32_e32 v231, v177, v161
	ds_read2_b32 v[176:177], v229 offset0:32 offset1:34
	s_waitcnt lgkmcnt(11)
	v_fmac_f32_e32 v230, v178, v162
	v_fmac_f32_e32 v231, v179, v163
	ds_read2_b32 v[178:179], v229 offset0:36 offset1:38
	s_waitcnt lgkmcnt(11)
	v_fmac_f32_e32 v230, v180, v164
	v_fmac_f32_e32 v231, v181, v165
	ds_read2_b32 v[180:181], v229 offset0:40 offset1:42
	s_waitcnt lgkmcnt(11)
	v_fmac_f32_e32 v230, v210, v166
	v_fmac_f32_e32 v231, v211, v167
	v_add_f32_e32 v230, v230, v231
	s_nop 1
	v_add_f32_dpp v232, v230, v230 quad_perm:[1,0,3,2] row_mask:0xf bank_mask:0xf
	v_sub_f32_e32 v233, v167, v232
	v_cndmask_b32_e64 v167, v167, v233, s[4:5]
	ds_read2_b32 v[210:211], v229 offset0:44 offset1:46
	s_waitcnt lgkmcnt(11)
	v_mul_f32_e32 v230, v212, v136
	v_mul_f32_e32 v231, v213, v137
	ds_read2_b32 v[212:213], v229 offset0:48 offset1:50
	s_waitcnt lgkmcnt(11)
	v_fmac_f32_e32 v230, v214, v138
	v_fmac_f32_e32 v231, v215, v139
	ds_read2_b32 v[214:215], v229 offset0:52 offset1:54
	s_waitcnt lgkmcnt(11)
	v_fmac_f32_e32 v230, v216, v140
	v_fmac_f32_e32 v231, v217, v141
	ds_read2_b32 v[216:217], v229 offset0:56 offset1:58
	s_waitcnt lgkmcnt(11)
	v_fmac_f32_e32 v230, v224, v142
	v_fmac_f32_e32 v231, v225, v143
	ds_read2_b32 v[224:225], v229 offset0:60 offset1:62
	s_waitcnt lgkmcnt(11)
	v_fmac_f32_e32 v230, v168, v144
	v_fmac_f32_e32 v231, v169, v145
	s_waitcnt lgkmcnt(10)
	v_fmac_f32_e32 v230, v170, v146
	v_fmac_f32_e32 v231, v171, v147
	s_waitcnt lgkmcnt(9)
	v_fmac_f32_e32 v230, v172, v148
	v_fmac_f32_e32 v231, v173, v149
	s_waitcnt lgkmcnt(8)
	v_fmac_f32_e32 v230, v174, v150
	v_fmac_f32_e32 v231, v175, v151
	s_waitcnt lgkmcnt(7)
	v_fmac_f32_e32 v230, v176, v152
	v_fmac_f32_e32 v231, v177, v153
	s_waitcnt lgkmcnt(6)
	v_fmac_f32_e32 v230, v178, v154
	v_fmac_f32_e32 v231, v179, v155
	s_waitcnt lgkmcnt(5)
	v_fmac_f32_e32 v230, v180, v156
	v_fmac_f32_e32 v231, v181, v157
	s_waitcnt lgkmcnt(4)
	v_fmac_f32_e32 v230, v210, v158
	v_fmac_f32_e32 v231, v211, v159
	s_waitcnt lgkmcnt(3)
	v_fmac_f32_e32 v230, v212, v160
	v_fmac_f32_e32 v231, v213, v161
	s_waitcnt lgkmcnt(2)
	v_fmac_f32_e32 v230, v214, v162
	v_fmac_f32_e32 v231, v215, v163
	s_waitcnt lgkmcnt(1)
	v_fmac_f32_e32 v230, v216, v164
	v_fmac_f32_e32 v231, v217, v165
	s_waitcnt lgkmcnt(0)
	v_fmac_f32_e32 v230, v224, v166
	v_fmac_f32_e32 v231, v225, v167
	v_add_f32_e32 v230, v230, v231
	s_nop 1
	v_add_f32_dpp v232, v230, v230 quad_perm:[1,0,3,2] row_mask:0xf bank_mask:0xf
	v_sub_f32_e32 v233, v167, v232
	v_cndmask_b32_e64 v167, v167, v233, s[8:9]
	ds_write_b32 v44, v136 offset:0
	ds_write_b32 v44, v137 offset:520
	ds_write_b32 v44, v138 offset:1040
	ds_write_b32 v44, v139 offset:1560
	ds_write_b32 v44, v140 offset:2080
	ds_write_b32 v44, v141 offset:2600
	ds_write_b32 v44, v142 offset:3120
	ds_write_b32 v44, v143 offset:3640
	ds_write_b32 v44, v144 offset:4160
	ds_write_b32 v44, v145 offset:4680
	ds_write_b32 v44, v146 offset:5200
	ds_write_b32 v44, v147 offset:5720
	ds_write_b32 v44, v148 offset:6240
	ds_write_b32 v44, v149 offset:6760
	ds_write_b32 v44, v150 offset:7280
	s_waitcnt lgkmcnt(0)
	ds_write_b32 v44, v151 offset:7800
	ds_write_b32 v44, v152 offset:8320
	ds_write_b32 v44, v153 offset:8840
	ds_write_b32 v44, v154 offset:9360
	ds_write_b32 v44, v155 offset:9880
	ds_write_b32 v44, v156 offset:10400
	ds_write_b32 v44, v157 offset:10920
	ds_write_b32 v44, v158 offset:11440
	ds_write_b32 v44, v159 offset:11960
	ds_write_b32 v44, v160 offset:12480
	ds_write_b32 v44, v161 offset:13000
	ds_write_b32 v44, v162 offset:13520
	ds_write_b32 v44, v163 offset:14040
	ds_write_b32 v44, v164 offset:14560
	ds_write_b32 v44, v165 offset:15080
	ds_write_b32 v44, v166 offset:15600
	ds_write_b32 v44, v167 offset:16120
	s_branch .LBB0_473
.Ltramp_736:
	s_branch .LBB0_736
.Ltramp_132:
	s_branch .LBB0_132
.Ltramp_131:
	s_branch .LBB0_131
.Ltramp_130:
	s_branch .LBB0_130
.LBB0_463:
	s_mov_b64 s[8:9], 0
